# gemm8: first k-tile peeled with C=0 (128 accumulator-zeroing movs per tile removed) on top of the v66 stack
# speedup vs baseline: 1.0085x; 1.0041x over previous
; #define MFMA16(a, b, c) __builtin_amdgcn_mfma_f32_16x16x32_bf16((a), (b), (c), 0, 0, 0)
; #define G8_STAGE(buf_, ap_, bp_) G8_STAGE_R(buf_, ap_, bp_, 0, 4)
; template <class Epi>
; DI void gemm8_tile(const bf16_t* __restrict__ Ab, int lda, const bf16_t* __restrict__ Bb, int ldb, int K, int brow, int bcol, const Epi epi,
;                    bool staged, bool has_next, const bf16_t* __restrict__ Abn, const bf16_t* __restrict__ Bbn) {
;     ...
;   f32x4 acc[8][4];
; #pragma unroll
;   for (int m = 0; m < 8; ++m)
; #pragma unroll
;     for (int n = 0; n < 4; ++n) acc[m][n] = (f32x4){0.f, 0.f, 0.f, 0.f};
;   const int nt = K / 64;
;   if (!staged) {
;     G8_STAGE(0, Ab, Bb);
;     asm volatile("s_waitcnt vmcnt(0)" ::: "memory");
;     __syncthreads();
;   }
;   for (int t = 0; t < nt; ++t) {
;     const int cur = t & 1;
;     const unsigned char* sa = smem + cur * G8_STAGE_B;
;     const unsigned char* sb = sa + G8_TILE_B;
; #pragma unroll
;     for (int ks = 0; ks < 2; ++ks) {
;       bf16x8 At[8], Bf[4];
;       Bf[0] = *(const bf16x8*)(sb + lds_byte2(wc * 64 + fr, ks * 32 + fq * 8));
;       At[0] = *(const bf16x8*)(sa + lds_byte2(wr * 128 + fr, ks * 32 + fq * 8));
; #pragma unroll
;       for (int n = 1; n < 4; ++n) Bf[n] = *(const bf16x8*)(sb + lds_byte2(wc * 64 + n * 16 + fr, ks * 32 + fq * 8));
; #pragma unroll
;       for (int m = 1; m < 8; ++m) At[m] = *(const bf16x8*)(sa + lds_byte2(wr * 128 + m * 16 + fr, ks * 32 + fq * 8));
;       {
;         __builtin_amdgcn_sched_barrier(0);
;         if (t + 1 < nt) { G8_STAGE_R(cur ^ 1, Ab + (t + 1) * 64, Bb + (t + 1) * 64, 2 * ks, 2 * ks + 2); }
;         else if (has_next) { G8_STAGE_R(0, Abn, Bbn, 2 * ks, 2 * ks + 2); }
;         __builtin_amdgcn_sched_barrier(0);
;       }
; #pragma unroll
;       for (int m = 0; m < 8; ++m)
; #pragma unroll
;         for (int n = 0; n < 4; ++n) acc[m][n] = MFMA16(At[m], Bf[n], acc[m][n]);
;       __builtin_amdgcn_sched_barrier(0);
;     }
;     asm volatile("s_waitcnt vmcnt(0)" ::: "memory");
;     __syncthreads();
;   }
.LBB0_461:
	v_readlane_b32 s0, v253, 4
	s_add_u32 s0, s0, s71
	v_readlane_b32 s1, v253, 5
	v_lshlrev_b64 v[212:213], 1, v[0:1]
	s_addc_u32 s1, s1, s78
	v_lshlrev_b64 v[214:215], 1, v[6:7]
	v_lshlrev_b64 v[146:147], 1, v[4:5]
	v_lshlrev_b64 v[148:149], 1, v[2:3]
	v_lshl_add_u64 v[130:131], s[0:1], 0, v[212:213]
	v_lshl_add_u64 v[132:133], s[0:1], 0, v[214:215]
	v_lshl_add_u64 v[134:135], s[0:1], 0, v[146:147]
	v_lshl_add_u64 v[136:137], s[0:1], 0, v[148:149]
	s_lshl_b32 s0, s59, 3
	s_add_i32 s0, s28, s0
	s_add_i32 s0, s0, s70
	s_lshl_b32 s1, s58, 3
	s_sub_i32 s0, s0, s1
	s_lshl_b32 s1, s0, 8
	s_mul_i32 s0, s0, 0x88000
	v_readlane_b32 s8, v253, 6
	v_and_b32_e32 v228, 63, v8
	v_and_b32_e32 v229, 3, v9
	v_ashrrev_i32_e32 v9, 8, v8
	v_and_b32_e32 v223, 15, v8
	v_and_b32_e32 v10, 48, v8
	v_lshlrev_b32_e32 v12, 2, v8
	v_lshlrev_b32_e32 v8, 6, v8
	s_mul_hi_i32 s1, s1, 0x880
	s_add_u32 s0, s8, s0
	v_readlane_b32 s8, v253, 7
	v_lshlrev_b32_e32 v11, 6, v223
	v_and_b32_e32 v12, 32, v12
	v_lshlrev_b32_e32 v153, 14, v9
	v_and_b32_e32 v8, 0x3c0, v8
	s_addc_u32 s1, s8, s1
	v_lshlrev_b32_e32 v151, 13, v229
	v_bitop3_b32 v152, v11, v12, v10 bitop3:0x36
	v_lshlrev_b32_e32 v230, 7, v9
	v_or_b32_e32 v150, 0x800, v153
	v_bitop3_b32 v158, v8, v12, v10 bitop3:0x36
	v_or_b32_e32 v167, 0x1000, v153
	v_or_b32_e32 v166, 0x1800, v153
	v_or_b32_e32 v165, 0x2000, v153
	v_or_b32_e32 v164, 0x2800, v153
	v_or_b32_e32 v163, 0x3000, v153
	v_or_b32_e32 v162, 0x3800, v153
	v_lshl_add_u64 v[138:139], s[0:1], 0, v[212:213]
	v_lshl_add_u64 v[140:141], s[0:1], 0, v[214:215]
	v_lshl_add_u64 v[142:143], s[0:1], 0, v[146:147]
	v_lshl_add_u64 v[144:145], s[0:1], 0, v[148:149]
	s_mov_b64 s[0:1], 0
	s_mov_b32 s14, 0
	v_add_u32_e32 v244, 0x10000, v157
	s_nop 0
	v_readfirstlane_b32 s56, v244
	s_mov_b32 m0, s56
	v_lshl_add_u64 v[160:161], v[144:145], 0, s[0:1]
	global_load_lds_dwordx4 v[160:161], off
	s_add_u32 m0, s56, 0x8000
	v_lshl_add_u64 v[160:161], v[136:137], 0, s[0:1]
	global_load_lds_dwordx4 v[160:161], off
	s_add_u32 m0, s56, 0x2000
	v_lshl_add_u64 v[160:161], v[142:143], 0, s[0:1]
	global_load_lds_dwordx4 v[160:161], off
	s_add_u32 m0, s56, 0xa000
	v_lshl_add_u64 v[160:161], v[134:135], 0, s[0:1]
	global_load_lds_dwordx4 v[160:161], off
	s_add_u32 m0, s56, 0x4000
	v_lshl_add_u64 v[160:161], v[140:141], 0, s[0:1]
	global_load_lds_dwordx4 v[160:161], off
	s_add_u32 m0, s56, 0xc000
	v_lshl_add_u64 v[160:161], v[132:133], 0, s[0:1]
	global_load_lds_dwordx4 v[160:161], off
	s_add_u32 m0, s56, 0x6000
	v_lshl_add_u64 v[160:161], v[138:139], 0, s[0:1]
	global_load_lds_dwordx4 v[160:161], off
	s_add_u32 m0, s56, 0xe000
	v_lshl_add_u64 v[160:161], v[130:131], 0, s[0:1]
	global_load_lds_dwordx4 v[160:161], off
	s_mov_b32 s56, 0
	v_add3_u32 v0, s56, v152, v151
	v_add3_u32 v159, s56, v152, v153
	v_add3_u32 v209, s56, v158, v167
	v_add3_u32 v240, s56, v158, v165
	v_add3_u32 v242, s56, v158, v163
	v_add3_u32 v208, s56, v158, v150
	v_add3_u32 v231, s56, v158, v166
	v_add3_u32 v241, s56, v158, v164
	v_add3_u32 v243, s56, v158, v162
	ds_read_b128 v[168:171], v0 offset:32768
	ds_read_b128 v[172:175], v0 offset:34816
	ds_read_b128 v[184:187], v159
	ds_read_b128 v[188:191], v208
	ds_read_b128 v[192:195], v209
	ds_read_b128 v[196:199], v231
	ds_read_b128 v[200:203], v240
	ds_read_b128 v[204:207], v241
	ds_read_b128 v[232:235], v242
	ds_read_b128 v[236:239], v243
	ds_read_b128 v[176:179], v0 offset:36864
	ds_read_b128 v[180:183], v0 offset:38912
	s_and_b32 s15, s14, 0x10000
	s_xor_b32 s56, s15, 0x10000
	v_add_u32_e32 v244, s56, v157
	s_nop 0
	v_readfirstlane_b32 s15, v244
	s_waitcnt lgkmcnt(8)
	v_mfma_f32_16x16x32_bf16 v[126:129], v[184:187], v[168:171], 0
	v_mfma_f32_16x16x32_bf16 v[122:125], v[184:187], v[172:175], 0
	v_mfma_f32_16x16x32_bf16 v[110:113], v[188:191], v[168:171], 0
	v_mfma_f32_16x16x32_bf16 v[106:109], v[188:191], v[172:175], 0
	s_waitcnt lgkmcnt(6)
	v_mfma_f32_16x16x32_bf16 v[94:97], v[192:195], v[168:171], 0
	v_mfma_f32_16x16x32_bf16 v[90:93], v[192:195], v[172:175], 0
	v_mfma_f32_16x16x32_bf16 v[78:81], v[196:199], v[168:171], 0
	v_mfma_f32_16x16x32_bf16 v[74:77], v[196:199], v[172:175], 0
	s_waitcnt lgkmcnt(4)
	v_mfma_f32_16x16x32_bf16 v[62:65], v[200:203], v[168:171], 0
	v_mfma_f32_16x16x32_bf16 v[58:61], v[200:203], v[172:175], 0
	v_mfma_f32_16x16x32_bf16 v[46:49], v[204:207], v[168:171], 0
	v_mfma_f32_16x16x32_bf16 v[42:45], v[204:207], v[172:175], 0
	s_waitcnt lgkmcnt(2)
	v_mfma_f32_16x16x32_bf16 v[30:33], v[232:235], v[168:171], 0
	v_mfma_f32_16x16x32_bf16 v[26:29], v[232:235], v[172:175], 0
	v_mfma_f32_16x16x32_bf16 v[14:17], v[236:239], v[168:171], 0
	v_mfma_f32_16x16x32_bf16 v[10:13], v[236:239], v[172:175], 0
	ds_read_b128 v[168:171], v0 offset:33792
	ds_read_b128 v[172:175], v0 offset:35840
	s_waitcnt lgkmcnt(2)
; #define MFMA16(a, b, c) __builtin_amdgcn_mfma_f32_16x16x32_bf16((a), (b), (c), 0, 0, 0)
; template <class Epi>
; DI void gemm8_tile(const bf16_t* __restrict__ Ab, int lda, const bf16_t* __restrict__ Bb, int ldb, int K, int brow, int bcol, const Epi epi,
;                    bool staged, bool has_next, const bf16_t* __restrict__ Abn, const bf16_t* __restrict__ Bbn) {
;     ...
;   for (int t = 0; t < nt; ++t) {
;     const int cur = t & 1;
;     const unsigned char* sa = smem + cur * G8_STAGE_B;
;     const unsigned char* sb = sa + G8_TILE_B;
; #pragma unroll
;     for (int ks = 0; ks < 2; ++ks) {
;       bf16x8 At[8], Bf[4];
;       Bf[0] = *(const bf16x8*)(sb + lds_byte2(wc * 64 + fr, ks * 32 + fq * 8));
;       At[0] = *(const bf16x8*)(sa + lds_byte2(wr * 128 + fr, ks * 32 + fq * 8));
; #pragma unroll
;       for (int n = 1; n < 4; ++n) Bf[n] = *(const bf16x8*)(sb + lds_byte2(wc * 64 + n * 16 + fr, ks * 32 + fq * 8));
; #pragma unroll
;       for (int m = 1; m < 8; ++m) At[m] = *(const bf16x8*)(sa + lds_byte2(wr * 128 + m * 16 + fr, ks * 32 + fq * 8));
;       {
;         __builtin_amdgcn_sched_barrier(0);
;         if (t + 1 < nt) { G8_STAGE_R(cur ^ 1, Ab + (t + 1) * 64, Bb + (t + 1) * 64, 2 * ks, 2 * ks + 2); }
;         else if (has_next) { G8_STAGE_R(0, Abn, Bbn, 2 * ks, 2 * ks + 2); }
;         __builtin_amdgcn_sched_barrier(0);
;       }
; #pragma unroll
;       for (int m = 0; m < 8; ++m)
; #pragma unroll
;         for (int n = 0; n < 4; ++n) acc[m][n] = MFMA16(At[m], Bf[n], acc[m][n]);
;       __builtin_amdgcn_sched_barrier(0);
;     }
;     asm volatile("s_waitcnt vmcnt(0)" ::: "memory");
;     __syncthreads();
;   }
	v_mfma_f32_16x16x32_bf16 v[118:121], v[184:187], v[176:179], 0
	v_mfma_f32_16x16x32_bf16 v[114:117], v[184:187], v[180:183], 0
	ds_read_b128 v[184:187], v159 offset:1024
	v_mfma_f32_16x16x32_bf16 v[102:105], v[188:191], v[176:179], 0
	v_mfma_f32_16x16x32_bf16 v[98:101], v[188:191], v[180:183], 0
	ds_read_b128 v[188:191], v208 offset:1024
	v_mfma_f32_16x16x32_bf16 v[86:89], v[192:195], v[176:179], 0
	v_mfma_f32_16x16x32_bf16 v[82:85], v[192:195], v[180:183], 0
	ds_read_b128 v[192:195], v209 offset:1024
	v_mfma_f32_16x16x32_bf16 v[70:73], v[196:199], v[176:179], 0
	v_mfma_f32_16x16x32_bf16 v[66:69], v[196:199], v[180:183], 0
	ds_read_b128 v[196:199], v231 offset:1024
	v_mfma_f32_16x16x32_bf16 v[54:57], v[200:203], v[176:179], 0
	v_mfma_f32_16x16x32_bf16 v[50:53], v[200:203], v[180:183], 0
	ds_read_b128 v[200:203], v240 offset:1024
	v_mfma_f32_16x16x32_bf16 v[38:41], v[204:207], v[176:179], 0
	v_mfma_f32_16x16x32_bf16 v[34:37], v[204:207], v[180:183], 0
	ds_read_b128 v[204:207], v241 offset:1024
	v_mfma_f32_16x16x32_bf16 v[22:25], v[232:235], v[176:179], 0
	v_mfma_f32_16x16x32_bf16 v[18:21], v[232:235], v[180:183], 0
	ds_read_b128 v[232:235], v242 offset:1024
	v_mfma_f32_16x16x32_bf16 v[6:9], v[236:239], v[176:179], 0
	v_mfma_f32_16x16x32_bf16 v[2:5], v[236:239], v[180:183], 0
	ds_read_b128 v[236:239], v243 offset:1024
	ds_read_b128 v[176:179], v0 offset:37888
	ds_read_b128 v[180:183], v0 offset:39936
	s_waitcnt lgkmcnt(8)
	v_mfma_f32_16x16x32_bf16 v[126:129], v[184:187], v[168:171], v[126:129]
	v_mfma_f32_16x16x32_bf16 v[122:125], v[184:187], v[172:175], v[122:125]
	v_add3_u32 v0, s56, v152, v151
	v_mfma_f32_16x16x32_bf16 v[110:113], v[188:191], v[168:171], v[110:113]
	v_mfma_f32_16x16x32_bf16 v[106:109], v[188:191], v[172:175], v[106:109]
	v_add3_u32 v159, s56, v152, v153
	s_waitcnt lgkmcnt(6)
	v_mfma_f32_16x16x32_bf16 v[94:97], v[192:195], v[168:171], v[94:97]
	v_mfma_f32_16x16x32_bf16 v[90:93], v[192:195], v[172:175], v[90:93]
	v_add3_u32 v209, s56, v158, v167
	v_mfma_f32_16x16x32_bf16 v[78:81], v[196:199], v[168:171], v[78:81]
	v_mfma_f32_16x16x32_bf16 v[74:77], v[196:199], v[172:175], v[74:77]
	v_add3_u32 v240, s56, v158, v165
	s_waitcnt lgkmcnt(4)
	v_mfma_f32_16x16x32_bf16 v[62:65], v[200:203], v[168:171], v[62:65]
	v_mfma_f32_16x16x32_bf16 v[58:61], v[200:203], v[172:175], v[58:61]
	v_add3_u32 v242, s56, v158, v163
	v_mfma_f32_16x16x32_bf16 v[46:49], v[204:207], v[168:171], v[46:49]
	v_mfma_f32_16x16x32_bf16 v[42:45], v[204:207], v[172:175], v[42:45]
	v_add3_u32 v208, s56, v158, v150
	s_waitcnt lgkmcnt(2)
	v_mfma_f32_16x16x32_bf16 v[30:33], v[232:235], v[168:171], v[30:33]
	v_mfma_f32_16x16x32_bf16 v[26:29], v[232:235], v[172:175], v[26:29]
	v_add3_u32 v231, s56, v158, v166
	v_mfma_f32_16x16x32_bf16 v[14:17], v[236:239], v[168:171], v[14:17]
	v_mfma_f32_16x16x32_bf16 v[10:13], v[236:239], v[172:175], v[10:13]
	v_add3_u32 v241, s56, v158, v164
	v_add3_u32 v243, s56, v158, v162
	s_waitcnt vmcnt(0) lgkmcnt(0)
	s_barrier
	s_add_u32 s0, s0, 0x80
	s_addc_u32 s1, s1, 0
	s_add_i32 s14, s14, 0x10000
	s_xor_b32 s56, s15, 0x10000
	ds_read_b128 v[168:171], v0 offset:32768
	ds_read_b128 v[172:175], v0 offset:34816
	v_mfma_f32_16x16x32_bf16 v[118:121], v[184:187], v[176:179], v[118:121]
	v_mfma_f32_16x16x32_bf16 v[114:117], v[184:187], v[180:183], v[114:117]
	ds_read_b128 v[184:187], v159
	s_mov_b32 m0, s56
	v_lshl_add_u64 v[160:161], v[144:145], 0, s[0:1]
	global_load_lds_dwordx4 v[160:161], off
	v_mfma_f32_16x16x32_bf16 v[102:105], v[188:191], v[176:179], v[102:105]
	v_mfma_f32_16x16x32_bf16 v[98:101], v[188:191], v[180:183], v[98:101]
	ds_read_b128 v[188:191], v208
	s_add_u32 m0, s56, 0x8000
	v_lshl_add_u64 v[160:161], v[136:137], 0, s[0:1]
	global_load_lds_dwordx4 v[160:161], off
	v_mfma_f32_16x16x32_bf16 v[86:89], v[192:195], v[176:179], v[86:89]
	v_mfma_f32_16x16x32_bf16 v[82:85], v[192:195], v[180:183], v[82:85]
	ds_read_b128 v[192:195], v209
	s_add_u32 m0, s56, 0x2000
	v_lshl_add_u64 v[160:161], v[142:143], 0, s[0:1]
	global_load_lds_dwordx4 v[160:161], off
	v_mfma_f32_16x16x32_bf16 v[70:73], v[196:199], v[176:179], v[70:73]
	v_mfma_f32_16x16x32_bf16 v[66:69], v[196:199], v[180:183], v[66:69]
	ds_read_b128 v[196:199], v231
	s_add_u32 m0, s56, 0xa000
	v_lshl_add_u64 v[160:161], v[134:135], 0, s[0:1]
	global_load_lds_dwordx4 v[160:161], off
	v_mfma_f32_16x16x32_bf16 v[54:57], v[200:203], v[176:179], v[54:57]
	v_mfma_f32_16x16x32_bf16 v[50:53], v[200:203], v[180:183], v[50:53]
	ds_read_b128 v[200:203], v240
	s_add_u32 m0, s56, 0x4000
	v_lshl_add_u64 v[160:161], v[140:141], 0, s[0:1]
	global_load_lds_dwordx4 v[160:161], off
	v_mfma_f32_16x16x32_bf16 v[38:41], v[204:207], v[176:179], v[38:41]
	v_mfma_f32_16x16x32_bf16 v[34:37], v[204:207], v[180:183], v[34:37]
	ds_read_b128 v[204:207], v241
	s_add_u32 m0, s56, 0xc000
	v_lshl_add_u64 v[160:161], v[132:133], 0, s[0:1]
	global_load_lds_dwordx4 v[160:161], off
	v_mfma_f32_16x16x32_bf16 v[22:25], v[232:235], v[176:179], v[22:25]
	v_mfma_f32_16x16x32_bf16 v[18:21], v[232:235], v[180:183], v[18:21]
	ds_read_b128 v[232:235], v242
	s_add_u32 m0, s56, 0x6000
	v_lshl_add_u64 v[160:161], v[138:139], 0, s[0:1]
	global_load_lds_dwordx4 v[160:161], off
	v_mfma_f32_16x16x32_bf16 v[6:9], v[236:239], v[176:179], v[6:9]
	v_mfma_f32_16x16x32_bf16 v[2:5], v[236:239], v[180:183], v[2:5]
	ds_read_b128 v[236:239], v243
	s_add_u32 m0, s56, 0xe000
	v_lshl_add_u64 v[160:161], v[130:131], 0, s[0:1]
	global_load_lds_dwordx4 v[160:161], off
	ds_read_b128 v[176:179], v0 offset:36864
	ds_read_b128 v[180:183], v0 offset:38912

; DI int opaque_tid512() { int t = threadIdx.x; asm volatile("" : "+v"(t)); return t; }
; #define MFMA16(a, b, c) __builtin_amdgcn_mfma_f32_16x16x32_bf16((a), (b), (c), 0, 0, 0)
; #define G8_STAGE(buf_, ap_, bp_) G8_STAGE_R(buf_, ap_, bp_, 0, 4)
; template <class Epi>
; DI void gemm8_tile(const bf16_t* __restrict__ Ab, int lda, const bf16_t* __restrict__ Bb, int ldb, int K, int brow, int bcol, const Epi epi,
;                    bool staged, bool has_next, const bf16_t* __restrict__ Abn, const bf16_t* __restrict__ Bbn) {
;   const int tid = opaque_tid512(), wid = tid >> 6, lane = tid & 63, wr = wid >> 2, wc = wid & 3, fr = lane & 15, fq = lane >> 4;
;   unsigned aoff[4], boff[4];
; #pragma unroll
;   for (int i = 0; i < 4; ++i) { int R, C; stage_rc2(wid * 1024 + i * 8192 + lane * 16, R, C); aoff[i] = (unsigned)R * (unsigned)lda + (unsigned)C; boff[i] = (unsigned)R * (unsigned)ldb + (unsigned)C; }
;     ...
;   f32x4 acc[8][4];
; #pragma unroll
;   for (int m = 0; m < 8; ++m)
; #pragma unroll
;     for (int n = 0; n < 4; ++n) acc[m][n] = (f32x4){0.f, 0.f, 0.f, 0.f};
;   const int nt = K / 64;
;   if (!staged) {
;     G8_STAGE(0, Ab, Bb);
;     asm volatile("s_waitcnt vmcnt(0)" ::: "memory");
;     __syncthreads();
;   }
;   for (int t = 0; t < nt; ++t) {
;     const int cur = t & 1;
;     const unsigned char* sa = smem + cur * G8_STAGE_B;
;     const unsigned char* sb = sa + G8_TILE_B;
; #pragma unroll
;     for (int ks = 0; ks < 2; ++ks) {
;       bf16x8 At[8], Bf[4];
;       Bf[0] = *(const bf16x8*)(sb + lds_byte2(wc * 64 + fr, ks * 32 + fq * 8));
;       At[0] = *(const bf16x8*)(sa + lds_byte2(wr * 128 + fr, ks * 32 + fq * 8));
; #pragma unroll
;       for (int n = 1; n < 4; ++n) Bf[n] = *(const bf16x8*)(sb + lds_byte2(wc * 64 + n * 16 + fr, ks * 32 + fq * 8));
; #pragma unroll
;       for (int m = 1; m < 8; ++m) At[m] = *(const bf16x8*)(sa + lds_byte2(wr * 128 + m * 16 + fr, ks * 32 + fq * 8));
;       {
;         __builtin_amdgcn_sched_barrier(0);
;         if (t + 1 < nt) { G8_STAGE_R(cur ^ 1, Ab + (t + 1) * 64, Bb + (t + 1) * 64, 2 * ks, 2 * ks + 2); }
;         else if (has_next) { G8_STAGE_R(0, Abn, Bbn, 2 * ks, 2 * ks + 2); }
;         __builtin_amdgcn_sched_barrier(0);
;       }
; #pragma unroll
;       for (int m = 0; m < 8; ++m)
; #pragma unroll
;         for (int n = 0; n < 4; ++n) acc[m][n] = MFMA16(At[m], Bf[n], acc[m][n]);
.LBB0_482:
	s_lshl_b32 s0, s71, 3
	s_add_i32 s0, s28, s0
	s_add_i32 s0, s0, s75
	s_lshl_b32 s1, s70, 3
	s_sub_i32 s0, s0, s1
	s_lshl_b32 s1, s0, 8
	s_mul_i32 s0, s0, 0x168000
	s_mul_hi_i32 s1, s1, 0x1680
	s_add_u32 s0, s91, s0
	v_lshlrev_b64 v[178:179], 1, v[4:5]
	s_addc_u32 s1, s72, s1
	v_lshlrev_b64 v[180:181], 1, v[2:3]
	v_lshlrev_b64 v[194:195], 1, v[6:7]
	v_lshlrev_b64 v[196:197], 1, v[0:1]
	v_and_b32_e32 v198, 15, v8
	v_lshl_add_u64 v[130:131], s[0:1], 0, v[178:179]
	v_lshl_add_u64 v[132:133], s[0:1], 0, v[180:181]
	v_lshl_add_u64 v[134:135], s[0:1], 0, v[194:195]
	v_lshl_add_u64 v[136:137], s[0:1], 0, v[196:197]
	v_readlane_b32 s0, v253, 8
	v_and_b32_e32 v206, 63, v8
	v_ashrrev_i32_e32 v10, 8, v8
	v_and_b32_e32 v204, 3, v9
	v_and_b32_e32 v9, 48, v8
	v_lshlrev_b32_e32 v199, 2, v198
	v_lshlrev_b32_e32 v8, 6, v8
	s_add_u32 s0, s0, s78
	v_readlane_b32 s1, v253, 9
	v_lshlrev_b32_e32 v11, 6, v198
	v_and_b32_e32 v12, 32, v199
	v_lshlrev_b32_e32 v156, 14, v10
	v_and_b32_e32 v8, 0x3c0, v8
	s_addc_u32 s1, s1, s79
	v_lshlrev_b32_e32 v153, 13, v204
	v_bitop3_b32 v155, v11, v12, v9 bitop3:0x36
	v_lshlrev_b32_e32 v205, 7, v10
	v_or_b32_e32 v150, 0x800, v156
	v_bitop3_b32 v154, v8, v12, v9 bitop3:0x36
	v_or_b32_e32 v152, 0x1000, v156
	v_or_b32_e32 v151, 0x1800, v156
	v_or_b32_e32 v149, 0x2000, v156
	v_or_b32_e32 v148, 0x2800, v156
	v_or_b32_e32 v147, 0x3000, v156
	v_or_b32_e32 v146, 0x3800, v156
	v_lshl_add_u64 v[138:139], s[0:1], 0, v[178:179]
	v_lshl_add_u64 v[140:141], s[0:1], 0, v[180:181]
	v_lshl_add_u64 v[142:143], s[0:1], 0, v[194:195]
	v_lshl_add_u64 v[144:145], s[0:1], 0, v[196:197]
	s_mov_b64 s[0:1], 0
	s_mov_b32 s56, 0
	v_add_u32_e32 v244, 0x10000, v185
	s_nop 0
	v_readfirstlane_b32 s58, v244
	s_mov_b32 m0, s58
	v_lshl_add_u64 v[208:209], v[130:131], 0, s[0:1]
	global_load_lds_dwordx4 v[208:209], off
	s_add_u32 m0, s58, 0x8000
	v_lshl_add_u64 v[208:209], v[138:139], 0, s[0:1]
	global_load_lds_dwordx4 v[208:209], off
	s_add_u32 m0, s58, 0x2000
	v_lshl_add_u64 v[208:209], v[132:133], 0, s[0:1]
	global_load_lds_dwordx4 v[208:209], off
	s_add_u32 m0, s58, 0xa000
	v_lshl_add_u64 v[208:209], v[140:141], 0, s[0:1]
	global_load_lds_dwordx4 v[208:209], off
	s_add_u32 m0, s58, 0x4000
	v_lshl_add_u64 v[208:209], v[134:135], 0, s[0:1]
	global_load_lds_dwordx4 v[208:209], off
	s_add_u32 m0, s58, 0xc000
	v_lshl_add_u64 v[208:209], v[142:143], 0, s[0:1]
	global_load_lds_dwordx4 v[208:209], off
	s_add_u32 m0, s58, 0x6000
	v_lshl_add_u64 v[208:209], v[136:137], 0, s[0:1]
	global_load_lds_dwordx4 v[208:209], off
	s_add_u32 m0, s58, 0xe000
	v_lshl_add_u64 v[208:209], v[144:145], 0, s[0:1]
	global_load_lds_dwordx4 v[208:209], off
	s_mov_b32 s58, 0
	v_add3_u32 v0, s58, v155, v153
	v_add3_u32 v157, s58, v155, v156
	v_add3_u32 v238, s58, v154, v152
	v_add3_u32 v240, s58, v154, v149
	v_add3_u32 v242, s58, v154, v147
	v_add3_u32 v207, s58, v154, v150
	v_add3_u32 v239, s58, v154, v151
	v_add3_u32 v241, s58, v154, v148
	v_add3_u32 v243, s58, v154, v146
	ds_read_b128 v[158:161], v0 offset:32768
	ds_read_b128 v[162:165], v0 offset:34816
	ds_read_b128 v[174:177], v157
	ds_read_b128 v[186:189], v207
	ds_read_b128 v[190:193], v238
	ds_read_b128 v[212:215], v239
	ds_read_b128 v[222:225], v240
	ds_read_b128 v[226:229], v241
	ds_read_b128 v[230:233], v242
	ds_read_b128 v[234:237], v243
	ds_read_b128 v[166:169], v0 offset:36864
	ds_read_b128 v[170:173], v0 offset:38912
	s_and_b32 s57, s56, 0x10000
	s_xor_b32 s58, s57, 0x10000
	v_add_u32_e32 v244, s58, v185
	s_nop 0
	v_readfirstlane_b32 s57, v244
	s_waitcnt lgkmcnt(8)
	v_mfma_f32_16x16x32_bf16 v[126:129], v[174:177], v[158:161], 0
	v_mfma_f32_16x16x32_bf16 v[122:125], v[174:177], v[162:165], 0
	v_mfma_f32_16x16x32_bf16 v[110:113], v[186:189], v[158:161], 0
	v_mfma_f32_16x16x32_bf16 v[106:109], v[186:189], v[162:165], 0
	s_waitcnt lgkmcnt(6)
	v_mfma_f32_16x16x32_bf16 v[94:97], v[190:193], v[158:161], 0
	v_mfma_f32_16x16x32_bf16 v[90:93], v[190:193], v[162:165], 0
	v_mfma_f32_16x16x32_bf16 v[78:81], v[212:215], v[158:161], 0
	v_mfma_f32_16x16x32_bf16 v[74:77], v[212:215], v[162:165], 0
	s_waitcnt lgkmcnt(4)
	v_mfma_f32_16x16x32_bf16 v[62:65], v[222:225], v[158:161], 0
	v_mfma_f32_16x16x32_bf16 v[58:61], v[222:225], v[162:165], 0
	v_mfma_f32_16x16x32_bf16 v[46:49], v[226:229], v[158:161], 0
	v_mfma_f32_16x16x32_bf16 v[42:45], v[226:229], v[162:165], 0
	s_waitcnt lgkmcnt(2)
	v_mfma_f32_16x16x32_bf16 v[30:33], v[230:233], v[158:161], 0
	v_mfma_f32_16x16x32_bf16 v[26:29], v[230:233], v[162:165], 0
	v_mfma_f32_16x16x32_bf16 v[14:17], v[234:237], v[158:161], 0
	v_mfma_f32_16x16x32_bf16 v[10:13], v[234:237], v[162:165], 0
	ds_read_b128 v[158:161], v0 offset:33792
	ds_read_b128 v[162:165], v0 offset:35840
	s_waitcnt lgkmcnt(2)
; #define MFMA16(a, b, c) __builtin_amdgcn_mfma_f32_16x16x32_bf16((a), (b), (c), 0, 0, 0)
; template <class Epi>
; DI void gemm8_tile(const bf16_t* __restrict__ Ab, int lda, const bf16_t* __restrict__ Bb, int ldb, int K, int brow, int bcol, const Epi epi,
;                    bool staged, bool has_next, const bf16_t* __restrict__ Abn, const bf16_t* __restrict__ Bbn) {
;     ...
;   for (int t = 0; t < nt; ++t) {
;     const int cur = t & 1;
;     const unsigned char* sa = smem + cur * G8_STAGE_B;
;     const unsigned char* sb = sa + G8_TILE_B;
; #pragma unroll
;     for (int ks = 0; ks < 2; ++ks) {
;       bf16x8 At[8], Bf[4];
;       Bf[0] = *(const bf16x8*)(sb + lds_byte2(wc * 64 + fr, ks * 32 + fq * 8));
;       At[0] = *(const bf16x8*)(sa + lds_byte2(wr * 128 + fr, ks * 32 + fq * 8));
; #pragma unroll
;       for (int n = 1; n < 4; ++n) Bf[n] = *(const bf16x8*)(sb + lds_byte2(wc * 64 + n * 16 + fr, ks * 32 + fq * 8));
; #pragma unroll
;       for (int m = 1; m < 8; ++m) At[m] = *(const bf16x8*)(sa + lds_byte2(wr * 128 + m * 16 + fr, ks * 32 + fq * 8));
;       {
;         __builtin_amdgcn_sched_barrier(0);
;         if (t + 1 < nt) { G8_STAGE_R(cur ^ 1, Ab + (t + 1) * 64, Bb + (t + 1) * 64, 2 * ks, 2 * ks + 2); }
;         else if (has_next) { G8_STAGE_R(0, Abn, Bbn, 2 * ks, 2 * ks + 2); }
;         __builtin_amdgcn_sched_barrier(0);
;       }
; #pragma unroll
;       for (int m = 0; m < 8; ++m)
; #pragma unroll
;         for (int n = 0; n < 4; ++n) acc[m][n] = MFMA16(At[m], Bf[n], acc[m][n]);
;       __builtin_amdgcn_sched_barrier(0);
;     }
;     asm volatile("s_waitcnt vmcnt(0)" ::: "memory");
;     __syncthreads();
	v_mfma_f32_16x16x32_bf16 v[118:121], v[174:177], v[166:169], 0
	v_mfma_f32_16x16x32_bf16 v[114:117], v[174:177], v[170:173], 0
	ds_read_b128 v[174:177], v157 offset:1024
	v_mfma_f32_16x16x32_bf16 v[102:105], v[186:189], v[166:169], 0
	v_mfma_f32_16x16x32_bf16 v[98:101], v[186:189], v[170:173], 0
	ds_read_b128 v[186:189], v207 offset:1024
	v_mfma_f32_16x16x32_bf16 v[86:89], v[190:193], v[166:169], 0
	v_mfma_f32_16x16x32_bf16 v[82:85], v[190:193], v[170:173], 0
	ds_read_b128 v[190:193], v238 offset:1024
	v_mfma_f32_16x16x32_bf16 v[70:73], v[212:215], v[166:169], 0
	v_mfma_f32_16x16x32_bf16 v[66:69], v[212:215], v[170:173], 0
	ds_read_b128 v[212:215], v239 offset:1024
	v_mfma_f32_16x16x32_bf16 v[54:57], v[222:225], v[166:169], 0
	v_mfma_f32_16x16x32_bf16 v[50:53], v[222:225], v[170:173], 0
	ds_read_b128 v[222:225], v240 offset:1024
	v_mfma_f32_16x16x32_bf16 v[38:41], v[226:229], v[166:169], 0
	v_mfma_f32_16x16x32_bf16 v[34:37], v[226:229], v[170:173], 0
	ds_read_b128 v[226:229], v241 offset:1024
	v_mfma_f32_16x16x32_bf16 v[22:25], v[230:233], v[166:169], 0
	v_mfma_f32_16x16x32_bf16 v[18:21], v[230:233], v[170:173], 0
	ds_read_b128 v[230:233], v242 offset:1024
	v_mfma_f32_16x16x32_bf16 v[6:9], v[234:237], v[166:169], 0
	v_mfma_f32_16x16x32_bf16 v[2:5], v[234:237], v[170:173], 0
	ds_read_b128 v[234:237], v243 offset:1024
	ds_read_b128 v[166:169], v0 offset:37888
	ds_read_b128 v[170:173], v0 offset:39936
	s_waitcnt lgkmcnt(8)
	v_mfma_f32_16x16x32_bf16 v[126:129], v[174:177], v[158:161], v[126:129]
	v_mfma_f32_16x16x32_bf16 v[122:125], v[174:177], v[162:165], v[122:125]
	v_add3_u32 v0, s58, v155, v153
	v_mfma_f32_16x16x32_bf16 v[110:113], v[186:189], v[158:161], v[110:113]
	v_mfma_f32_16x16x32_bf16 v[106:109], v[186:189], v[162:165], v[106:109]
	v_add3_u32 v157, s58, v155, v156
	s_waitcnt lgkmcnt(6)
	v_mfma_f32_16x16x32_bf16 v[94:97], v[190:193], v[158:161], v[94:97]
	v_mfma_f32_16x16x32_bf16 v[90:93], v[190:193], v[162:165], v[90:93]
	v_add3_u32 v238, s58, v154, v152
	v_mfma_f32_16x16x32_bf16 v[78:81], v[212:215], v[158:161], v[78:81]
	v_mfma_f32_16x16x32_bf16 v[74:77], v[212:215], v[162:165], v[74:77]
	v_add3_u32 v240, s58, v154, v149
	s_waitcnt lgkmcnt(4)
	v_mfma_f32_16x16x32_bf16 v[62:65], v[222:225], v[158:161], v[62:65]
	v_mfma_f32_16x16x32_bf16 v[58:61], v[222:225], v[162:165], v[58:61]
	v_add3_u32 v242, s58, v154, v147
	v_mfma_f32_16x16x32_bf16 v[46:49], v[226:229], v[158:161], v[46:49]
	v_mfma_f32_16x16x32_bf16 v[42:45], v[226:229], v[162:165], v[42:45]
	v_add3_u32 v207, s58, v154, v150
	s_waitcnt lgkmcnt(2)
	v_mfma_f32_16x16x32_bf16 v[30:33], v[230:233], v[158:161], v[30:33]
	v_mfma_f32_16x16x32_bf16 v[26:29], v[230:233], v[162:165], v[26:29]
	v_add3_u32 v239, s58, v154, v151
	v_mfma_f32_16x16x32_bf16 v[14:17], v[234:237], v[158:161], v[14:17]
	v_mfma_f32_16x16x32_bf16 v[10:13], v[234:237], v[162:165], v[10:13]
	v_add3_u32 v241, s58, v154, v148
	v_add3_u32 v243, s58, v154, v146
	s_waitcnt vmcnt(0) lgkmcnt(0)
	s_barrier
	s_add_u32 s0, s0, 0x80
	s_addc_u32 s1, s1, 0
	s_add_i32 s56, s56, 0x10000
	s_xor_b32 s58, s57, 0x10000
	ds_read_b128 v[158:161], v0 offset:32768
	ds_read_b128 v[162:165], v0 offset:34816
	v_mfma_f32_16x16x32_bf16 v[118:121], v[174:177], v[166:169], v[118:121]
	v_mfma_f32_16x16x32_bf16 v[114:117], v[174:177], v[170:173], v[114:117]
	ds_read_b128 v[174:177], v157
	s_mov_b32 m0, s58
	v_lshl_add_u64 v[208:209], v[130:131], 0, s[0:1]
	global_load_lds_dwordx4 v[208:209], off
	v_mfma_f32_16x16x32_bf16 v[102:105], v[186:189], v[166:169], v[102:105]
	v_mfma_f32_16x16x32_bf16 v[98:101], v[186:189], v[170:173], v[98:101]
	ds_read_b128 v[186:189], v207
	s_add_u32 m0, s58, 0x8000
	v_lshl_add_u64 v[208:209], v[138:139], 0, s[0:1]
	global_load_lds_dwordx4 v[208:209], off
	v_mfma_f32_16x16x32_bf16 v[86:89], v[190:193], v[166:169], v[86:89]
	v_mfma_f32_16x16x32_bf16 v[82:85], v[190:193], v[170:173], v[82:85]
	ds_read_b128 v[190:193], v238
	s_add_u32 m0, s58, 0x2000
	v_lshl_add_u64 v[208:209], v[132:133], 0, s[0:1]
	global_load_lds_dwordx4 v[208:209], off
	v_mfma_f32_16x16x32_bf16 v[70:73], v[212:215], v[166:169], v[70:73]
	v_mfma_f32_16x16x32_bf16 v[66:69], v[212:215], v[170:173], v[66:69]
	ds_read_b128 v[212:215], v239
	s_add_u32 m0, s58, 0xa000
	v_lshl_add_u64 v[208:209], v[140:141], 0, s[0:1]
	global_load_lds_dwordx4 v[208:209], off
	v_mfma_f32_16x16x32_bf16 v[54:57], v[222:225], v[166:169], v[54:57]
	v_mfma_f32_16x16x32_bf16 v[50:53], v[222:225], v[170:173], v[50:53]
	ds_read_b128 v[222:225], v240
	s_add_u32 m0, s58, 0x4000
	v_lshl_add_u64 v[208:209], v[134:135], 0, s[0:1]
	global_load_lds_dwordx4 v[208:209], off
	v_mfma_f32_16x16x32_bf16 v[38:41], v[226:229], v[166:169], v[38:41]
	v_mfma_f32_16x16x32_bf16 v[34:37], v[226:229], v[170:173], v[34:37]
	ds_read_b128 v[226:229], v241
	s_add_u32 m0, s58, 0xc000
	v_lshl_add_u64 v[208:209], v[142:143], 0, s[0:1]
	global_load_lds_dwordx4 v[208:209], off
	v_mfma_f32_16x16x32_bf16 v[22:25], v[230:233], v[166:169], v[22:25]
	v_mfma_f32_16x16x32_bf16 v[18:21], v[230:233], v[170:173], v[18:21]
	ds_read_b128 v[230:233], v242
	s_add_u32 m0, s58, 0x6000
	v_lshl_add_u64 v[208:209], v[136:137], 0, s[0:1]
	global_load_lds_dwordx4 v[208:209], off
	v_mfma_f32_16x16x32_bf16 v[6:9], v[234:237], v[166:169], v[6:9]
	v_mfma_f32_16x16x32_bf16 v[2:5], v[234:237], v[170:173], v[2:5]
	ds_read_b128 v[234:237], v243
	s_add_u32 m0, s58, 0xe000
	v_lshl_add_u64 v[208:209], v[144:145], 0, s[0:1]
	global_load_lds_dwordx4 v[208:209], off
	ds_read_b128 v[166:169], v0 offset:36864
	ds_read_b128 v[170:173], v0 offset:38912

; DI int opaque_tid512() { int t = threadIdx.x; asm volatile("" : "+v"(t)); return t; }
; #define MFMA16(a, b, c) __builtin_amdgcn_mfma_f32_16x16x32_bf16((a), (b), (c), 0, 0, 0)
; #define G8_STAGE(buf_, ap_, bp_) G8_STAGE_R(buf_, ap_, bp_, 0, 4)
; template <class Epi>
; DI void gemm8_tile(const bf16_t* __restrict__ Ab, int lda, const bf16_t* __restrict__ Bb, int ldb, int K, int brow, int bcol, const Epi epi,
;                    bool staged, bool has_next, const bf16_t* __restrict__ Abn, const bf16_t* __restrict__ Bbn) {
;   const int tid = opaque_tid512(), wid = tid >> 6, lane = tid & 63, wr = wid >> 2, wc = wid & 3, fr = lane & 15, fq = lane >> 4;
;   unsigned aoff[4], boff[4];
; #pragma unroll
;   for (int i = 0; i < 4; ++i) { int R, C; stage_rc2(wid * 1024 + i * 8192 + lane * 16, R, C); aoff[i] = (unsigned)R * (unsigned)lda + (unsigned)C; boff[i] = (unsigned)R * (unsigned)ldb + (unsigned)C; }
;     ...
;   f32x4 acc[8][4];
; #pragma unroll
;   for (int m = 0; m < 8; ++m)
; #pragma unroll
;     for (int n = 0; n < 4; ++n) acc[m][n] = (f32x4){0.f, 0.f, 0.f, 0.f};
;   const int nt = K / 64;
;   if (!staged) {
;     G8_STAGE(0, Ab, Bb);
;     asm volatile("s_waitcnt vmcnt(0)" ::: "memory");
;     __syncthreads();
;   }
;   for (int t = 0; t < nt; ++t) {
;     const int cur = t & 1;
;     const unsigned char* sa = smem + cur * G8_STAGE_B;
;     const unsigned char* sb = sa + G8_TILE_B;
; #pragma unroll
;     for (int ks = 0; ks < 2; ++ks) {
;       bf16x8 At[8], Bf[4];
;       Bf[0] = *(const bf16x8*)(sb + lds_byte2(wc * 64 + fr, ks * 32 + fq * 8));
;       At[0] = *(const bf16x8*)(sa + lds_byte2(wr * 128 + fr, ks * 32 + fq * 8));
; #pragma unroll
;       for (int n = 1; n < 4; ++n) Bf[n] = *(const bf16x8*)(sb + lds_byte2(wc * 64 + n * 16 + fr, ks * 32 + fq * 8));
; #pragma unroll
;       for (int m = 1; m < 8; ++m) At[m] = *(const bf16x8*)(sa + lds_byte2(wr * 128 + m * 16 + fr, ks * 32 + fq * 8));
;       {
;         __builtin_amdgcn_sched_barrier(0);
;         if (t + 1 < nt) { G8_STAGE_R(cur ^ 1, Ab + (t + 1) * 64, Bb + (t + 1) * 64, 2 * ks, 2 * ks + 2); }
;         else if (has_next) { G8_STAGE_R(0, Abn, Bbn, 2 * ks, 2 * ks + 2); }
;         __builtin_amdgcn_sched_barrier(0);
;       }
; #pragma unroll
;       for (int m = 0; m < 8; ++m)
; #pragma unroll
;         for (int n = 0; n < 4; ++n) acc[m][n] = MFMA16(At[m], Bf[n], acc[m][n]);
.LBB0_649:
	s_add_u32 s0, s56, s79
	v_lshlrev_b64 v[190:191], 1, v[0:1]
	s_addc_u32 s1, s57, s81
	v_lshlrev_b64 v[192:193], 1, v[6:7]
	v_lshlrev_b64 v[178:179], 1, v[4:5]
	v_lshlrev_b64 v[180:181], 1, v[2:3]
	v_lshl_add_u64 v[130:131], s[0:1], 0, v[190:191]
	v_lshl_add_u64 v[132:133], s[0:1], 0, v[192:193]
	v_lshl_add_u64 v[134:135], s[0:1], 0, v[178:179]
	v_lshl_add_u64 v[136:137], s[0:1], 0, v[180:181]
	s_lshl_b32 s0, s59, 3
	s_add_i32 s0, s28, s0
	s_add_i32 s0, s0, s78
	s_lshl_b32 s1, s31, 3
	s_sub_i32 s0, s0, s1
	v_and_b32_e32 v200, 3, v8
	v_ashrrev_i32_e32 v8, 8, v195
	s_lshl_b32 s1, s0, 8
	s_mul_i32 s0, s0, 0x88000
	v_readlane_b32 s4, v253, 6
	v_and_b32_e32 v194, 15, v195
	v_lshlrev_b32_e32 v11, 2, v195
	v_lshlrev_b32_e32 v201, 7, v8
	v_lshlrev_b32_e32 v156, 14, v8
	v_lshlrev_b32_e32 v8, 6, v195
	s_mul_hi_i32 s1, s1, 0x880
	s_add_u32 s0, s4, s0
	v_readlane_b32 s4, v253, 7
	v_and_b32_e32 v9, 48, v195
	v_lshlrev_b32_e32 v10, 6, v194
	v_and_b32_e32 v11, 32, v11
	v_and_b32_e32 v8, 0x3c0, v8
	s_addc_u32 s1, s4, s1
	v_lshlrev_b32_e32 v153, 13, v200
	v_bitop3_b32 v155, v10, v11, v9 bitop3:0x36
	v_or_b32_e32 v150, 0x800, v156
	v_bitop3_b32 v154, v8, v11, v9 bitop3:0x36
	v_or_b32_e32 v152, 0x1000, v156
	v_or_b32_e32 v151, 0x1800, v156
	v_or_b32_e32 v149, 0x2000, v156
	v_or_b32_e32 v148, 0x2800, v156
	v_or_b32_e32 v147, 0x3000, v156
	v_or_b32_e32 v146, 0x3800, v156
	v_lshl_add_u64 v[138:139], s[0:1], 0, v[190:191]
	v_lshl_add_u64 v[140:141], s[0:1], 0, v[192:193]
	v_lshl_add_u64 v[142:143], s[0:1], 0, v[178:179]
	v_lshl_add_u64 v[144:145], s[0:1], 0, v[180:181]
	s_mov_b64 s[0:1], 0
	s_mov_b32 s14, 0
	v_add_u32_e32 v243, 0x10000, v185
	s_nop 0
	v_readfirstlane_b32 s31, v243
	s_mov_b32 m0, s31
	v_lshl_add_u64 v[234:235], v[144:145], 0, s[0:1]
	global_load_lds_dwordx4 v[234:235], off
	s_add_u32 m0, s31, 0x8000
	v_lshl_add_u64 v[234:235], v[136:137], 0, s[0:1]
	global_load_lds_dwordx4 v[234:235], off
	s_add_u32 m0, s31, 0x2000
	v_lshl_add_u64 v[234:235], v[142:143], 0, s[0:1]
	global_load_lds_dwordx4 v[234:235], off
	s_add_u32 m0, s31, 0xa000
	v_lshl_add_u64 v[234:235], v[134:135], 0, s[0:1]
	global_load_lds_dwordx4 v[234:235], off
	s_add_u32 m0, s31, 0x4000
	v_lshl_add_u64 v[234:235], v[140:141], 0, s[0:1]
	global_load_lds_dwordx4 v[234:235], off
	s_add_u32 m0, s31, 0xc000
	v_lshl_add_u64 v[234:235], v[132:133], 0, s[0:1]
	global_load_lds_dwordx4 v[234:235], off
	s_add_u32 m0, s31, 0x6000
	v_lshl_add_u64 v[234:235], v[138:139], 0, s[0:1]
	global_load_lds_dwordx4 v[234:235], off
	s_add_u32 m0, s31, 0xe000
	v_lshl_add_u64 v[234:235], v[130:131], 0, s[0:1]
	global_load_lds_dwordx4 v[234:235], off
	s_mov_b32 s31, 0
	v_add3_u32 v0, s31, v155, v153
	v_add3_u32 v157, s31, v155, v156
	v_add3_u32 v237, s31, v154, v152
	v_add3_u32 v239, s31, v154, v149
	v_add3_u32 v241, s31, v154, v147
	v_add3_u32 v236, s31, v154, v150
	v_add3_u32 v238, s31, v154, v151
	v_add3_u32 v240, s31, v154, v148
	v_add3_u32 v242, s31, v154, v146
	ds_read_b128 v[158:161], v0 offset:32768
	ds_read_b128 v[162:165], v0 offset:34816
	ds_read_b128 v[174:177], v157
	ds_read_b128 v[186:189], v236
	ds_read_b128 v[202:205], v237
	ds_read_b128 v[206:209], v238
	ds_read_b128 v[212:215], v239
	ds_read_b128 v[222:225], v240
	ds_read_b128 v[226:229], v241
	ds_read_b128 v[230:233], v242
	ds_read_b128 v[166:169], v0 offset:36864
	ds_read_b128 v[170:173], v0 offset:38912
	s_and_b32 s15, s14, 0x10000
	s_xor_b32 s31, s15, 0x10000
	v_add_u32_e32 v243, s31, v185
	s_nop 0
	v_readfirstlane_b32 s15, v243
	s_waitcnt lgkmcnt(8)
	v_mfma_f32_16x16x32_bf16 v[126:129], v[174:177], v[158:161], 0
	v_mfma_f32_16x16x32_bf16 v[122:125], v[174:177], v[162:165], 0
	v_mfma_f32_16x16x32_bf16 v[110:113], v[186:189], v[158:161], 0
	v_mfma_f32_16x16x32_bf16 v[106:109], v[186:189], v[162:165], 0
	s_waitcnt lgkmcnt(6)
	v_mfma_f32_16x16x32_bf16 v[94:97], v[202:205], v[158:161], 0
	v_mfma_f32_16x16x32_bf16 v[90:93], v[202:205], v[162:165], 0
	v_mfma_f32_16x16x32_bf16 v[78:81], v[206:209], v[158:161], 0
	v_mfma_f32_16x16x32_bf16 v[74:77], v[206:209], v[162:165], 0
	s_waitcnt lgkmcnt(4)
	v_mfma_f32_16x16x32_bf16 v[62:65], v[212:215], v[158:161], 0
	v_mfma_f32_16x16x32_bf16 v[58:61], v[212:215], v[162:165], 0
	v_mfma_f32_16x16x32_bf16 v[46:49], v[222:225], v[158:161], 0
	v_mfma_f32_16x16x32_bf16 v[42:45], v[222:225], v[162:165], 0
	s_waitcnt lgkmcnt(2)
	v_mfma_f32_16x16x32_bf16 v[30:33], v[226:229], v[158:161], 0
	v_mfma_f32_16x16x32_bf16 v[26:29], v[226:229], v[162:165], 0
	v_mfma_f32_16x16x32_bf16 v[14:17], v[230:233], v[158:161], 0
	v_mfma_f32_16x16x32_bf16 v[10:13], v[230:233], v[162:165], 0
	ds_read_b128 v[158:161], v0 offset:33792
	ds_read_b128 v[162:165], v0 offset:35840
	s_waitcnt lgkmcnt(2)
; #define MFMA16(a, b, c) __builtin_amdgcn_mfma_f32_16x16x32_bf16((a), (b), (c), 0, 0, 0)
; template <class Epi>
; DI void gemm8_tile(const bf16_t* __restrict__ Ab, int lda, const bf16_t* __restrict__ Bb, int ldb, int K, int brow, int bcol, const Epi epi,
;                    bool staged, bool has_next, const bf16_t* __restrict__ Abn, const bf16_t* __restrict__ Bbn) {
;     ...
;   for (int t = 0; t < nt; ++t) {
;     const int cur = t & 1;
;     const unsigned char* sa = smem + cur * G8_STAGE_B;
;     const unsigned char* sb = sa + G8_TILE_B;
; #pragma unroll
;     for (int ks = 0; ks < 2; ++ks) {
;       bf16x8 At[8], Bf[4];
;       Bf[0] = *(const bf16x8*)(sb + lds_byte2(wc * 64 + fr, ks * 32 + fq * 8));
;       At[0] = *(const bf16x8*)(sa + lds_byte2(wr * 128 + fr, ks * 32 + fq * 8));
; #pragma unroll
;       for (int n = 1; n < 4; ++n) Bf[n] = *(const bf16x8*)(sb + lds_byte2(wc * 64 + n * 16 + fr, ks * 32 + fq * 8));
; #pragma unroll
;       for (int m = 1; m < 8; ++m) At[m] = *(const bf16x8*)(sa + lds_byte2(wr * 128 + m * 16 + fr, ks * 32 + fq * 8));
;       {
;         __builtin_amdgcn_sched_barrier(0);
;         if (t + 1 < nt) { G8_STAGE_R(cur ^ 1, Ab + (t + 1) * 64, Bb + (t + 1) * 64, 2 * ks, 2 * ks + 2); }
;         else if (has_next) { G8_STAGE_R(0, Abn, Bbn, 2 * ks, 2 * ks + 2); }
;         __builtin_amdgcn_sched_barrier(0);
;       }
; #pragma unroll
;       for (int m = 0; m < 8; ++m)
; #pragma unroll
;         for (int n = 0; n < 4; ++n) acc[m][n] = MFMA16(At[m], Bf[n], acc[m][n]);
;       __builtin_amdgcn_sched_barrier(0);
;     }
;     asm volatile("s_waitcnt vmcnt(0)" ::: "memory");
;     __syncthreads();
	v_mfma_f32_16x16x32_bf16 v[118:121], v[174:177], v[166:169], 0
	v_mfma_f32_16x16x32_bf16 v[114:117], v[174:177], v[170:173], 0
	ds_read_b128 v[174:177], v157 offset:1024
	v_mfma_f32_16x16x32_bf16 v[102:105], v[186:189], v[166:169], 0
	v_mfma_f32_16x16x32_bf16 v[98:101], v[186:189], v[170:173], 0
	ds_read_b128 v[186:189], v236 offset:1024
	v_mfma_f32_16x16x32_bf16 v[86:89], v[202:205], v[166:169], 0
	v_mfma_f32_16x16x32_bf16 v[82:85], v[202:205], v[170:173], 0
	ds_read_b128 v[202:205], v237 offset:1024
	v_mfma_f32_16x16x32_bf16 v[70:73], v[206:209], v[166:169], 0
	v_mfma_f32_16x16x32_bf16 v[66:69], v[206:209], v[170:173], 0
	ds_read_b128 v[206:209], v238 offset:1024
	v_mfma_f32_16x16x32_bf16 v[54:57], v[212:215], v[166:169], 0
	v_mfma_f32_16x16x32_bf16 v[50:53], v[212:215], v[170:173], 0
	ds_read_b128 v[212:215], v239 offset:1024
	v_mfma_f32_16x16x32_bf16 v[38:41], v[222:225], v[166:169], 0
	v_mfma_f32_16x16x32_bf16 v[34:37], v[222:225], v[170:173], 0
	ds_read_b128 v[222:225], v240 offset:1024
	v_mfma_f32_16x16x32_bf16 v[22:25], v[226:229], v[166:169], 0
	v_mfma_f32_16x16x32_bf16 v[18:21], v[226:229], v[170:173], 0
	ds_read_b128 v[226:229], v241 offset:1024
	v_mfma_f32_16x16x32_bf16 v[6:9], v[230:233], v[166:169], 0
	v_mfma_f32_16x16x32_bf16 v[2:5], v[230:233], v[170:173], 0
	ds_read_b128 v[230:233], v242 offset:1024
	ds_read_b128 v[166:169], v0 offset:37888
	ds_read_b128 v[170:173], v0 offset:39936
	s_waitcnt lgkmcnt(8)
	v_mfma_f32_16x16x32_bf16 v[126:129], v[174:177], v[158:161], v[126:129]
	v_mfma_f32_16x16x32_bf16 v[122:125], v[174:177], v[162:165], v[122:125]
	v_add3_u32 v0, s31, v155, v153
	v_mfma_f32_16x16x32_bf16 v[110:113], v[186:189], v[158:161], v[110:113]
	v_mfma_f32_16x16x32_bf16 v[106:109], v[186:189], v[162:165], v[106:109]
	v_add3_u32 v157, s31, v155, v156
	s_waitcnt lgkmcnt(6)
	v_mfma_f32_16x16x32_bf16 v[94:97], v[202:205], v[158:161], v[94:97]
	v_mfma_f32_16x16x32_bf16 v[90:93], v[202:205], v[162:165], v[90:93]
	v_add3_u32 v237, s31, v154, v152
	v_mfma_f32_16x16x32_bf16 v[78:81], v[206:209], v[158:161], v[78:81]
	v_mfma_f32_16x16x32_bf16 v[74:77], v[206:209], v[162:165], v[74:77]
	v_add3_u32 v239, s31, v154, v149
	s_waitcnt lgkmcnt(4)
	v_mfma_f32_16x16x32_bf16 v[62:65], v[212:215], v[158:161], v[62:65]
	v_mfma_f32_16x16x32_bf16 v[58:61], v[212:215], v[162:165], v[58:61]
	v_add3_u32 v241, s31, v154, v147
	v_mfma_f32_16x16x32_bf16 v[46:49], v[222:225], v[158:161], v[46:49]
	v_mfma_f32_16x16x32_bf16 v[42:45], v[222:225], v[162:165], v[42:45]
	v_add3_u32 v236, s31, v154, v150
	s_waitcnt lgkmcnt(2)
	v_mfma_f32_16x16x32_bf16 v[30:33], v[226:229], v[158:161], v[30:33]
	v_mfma_f32_16x16x32_bf16 v[26:29], v[226:229], v[162:165], v[26:29]
	v_add3_u32 v238, s31, v154, v151
	v_mfma_f32_16x16x32_bf16 v[14:17], v[230:233], v[158:161], v[14:17]
	v_mfma_f32_16x16x32_bf16 v[10:13], v[230:233], v[162:165], v[10:13]
	v_add3_u32 v240, s31, v154, v148
	v_add3_u32 v242, s31, v154, v146
	s_waitcnt vmcnt(0) lgkmcnt(0)
	s_barrier
	s_add_u32 s0, s0, 0x80
	s_addc_u32 s1, s1, 0
	s_add_i32 s14, s14, 0x10000
	s_xor_b32 s31, s15, 0x10000
	ds_read_b128 v[158:161], v0 offset:32768
	ds_read_b128 v[162:165], v0 offset:34816
	v_mfma_f32_16x16x32_bf16 v[118:121], v[174:177], v[166:169], v[118:121]
	v_mfma_f32_16x16x32_bf16 v[114:117], v[174:177], v[170:173], v[114:117]
	ds_read_b128 v[174:177], v157
	s_mov_b32 m0, s31
	v_lshl_add_u64 v[234:235], v[144:145], 0, s[0:1]
	global_load_lds_dwordx4 v[234:235], off
	v_mfma_f32_16x16x32_bf16 v[102:105], v[186:189], v[166:169], v[102:105]
	v_mfma_f32_16x16x32_bf16 v[98:101], v[186:189], v[170:173], v[98:101]
	ds_read_b128 v[186:189], v236
	s_add_u32 m0, s31, 0x8000
	v_lshl_add_u64 v[234:235], v[136:137], 0, s[0:1]
	global_load_lds_dwordx4 v[234:235], off
	v_mfma_f32_16x16x32_bf16 v[86:89], v[202:205], v[166:169], v[86:89]
	v_mfma_f32_16x16x32_bf16 v[82:85], v[202:205], v[170:173], v[82:85]
	ds_read_b128 v[202:205], v237
	s_add_u32 m0, s31, 0x2000
	v_lshl_add_u64 v[234:235], v[142:143], 0, s[0:1]
	global_load_lds_dwordx4 v[234:235], off
	v_mfma_f32_16x16x32_bf16 v[70:73], v[206:209], v[166:169], v[70:73]
	v_mfma_f32_16x16x32_bf16 v[66:69], v[206:209], v[170:173], v[66:69]
	ds_read_b128 v[206:209], v238
	s_add_u32 m0, s31, 0xa000
	v_lshl_add_u64 v[234:235], v[134:135], 0, s[0:1]
	global_load_lds_dwordx4 v[234:235], off
	v_mfma_f32_16x16x32_bf16 v[54:57], v[212:215], v[166:169], v[54:57]
	v_mfma_f32_16x16x32_bf16 v[50:53], v[212:215], v[170:173], v[50:53]
	ds_read_b128 v[212:215], v239
	s_add_u32 m0, s31, 0x4000
	v_lshl_add_u64 v[234:235], v[140:141], 0, s[0:1]
	global_load_lds_dwordx4 v[234:235], off
	v_mfma_f32_16x16x32_bf16 v[38:41], v[222:225], v[166:169], v[38:41]
	v_mfma_f32_16x16x32_bf16 v[34:37], v[222:225], v[170:173], v[34:37]
	ds_read_b128 v[222:225], v240
	s_add_u32 m0, s31, 0xc000
	v_lshl_add_u64 v[234:235], v[132:133], 0, s[0:1]
	global_load_lds_dwordx4 v[234:235], off
	v_mfma_f32_16x16x32_bf16 v[22:25], v[226:229], v[166:169], v[22:25]
	v_mfma_f32_16x16x32_bf16 v[18:21], v[226:229], v[170:173], v[18:21]
	ds_read_b128 v[226:229], v241
	s_add_u32 m0, s31, 0x6000
	v_lshl_add_u64 v[234:235], v[138:139], 0, s[0:1]
	global_load_lds_dwordx4 v[234:235], off
	v_mfma_f32_16x16x32_bf16 v[6:9], v[230:233], v[166:169], v[6:9]
	v_mfma_f32_16x16x32_bf16 v[2:5], v[230:233], v[170:173], v[2:5]
	ds_read_b128 v[230:233], v242
	s_add_u32 m0, s31, 0xe000
	v_lshl_add_u64 v[234:235], v[130:131], 0, s[0:1]
	global_load_lds_dwordx4 v[234:235], off
	ds_read_b128 v[166:169], v0 offset:36864
	ds_read_b128 v[170:173], v0 offset:38912

; DI int opaque_tid512() { int t = threadIdx.x; asm volatile("" : "+v"(t)); return t; }
; #define MFMA16(a, b, c) __builtin_amdgcn_mfma_f32_16x16x32_bf16((a), (b), (c), 0, 0, 0)
; #define G8_STAGE(buf_, ap_, bp_) G8_STAGE_R(buf_, ap_, bp_, 0, 4)
; template <class Epi>
; DI void gemm8_tile(const bf16_t* __restrict__ Ab, int lda, const bf16_t* __restrict__ Bb, int ldb, int K, int brow, int bcol, const Epi epi,
;                    bool staged, bool has_next, const bf16_t* __restrict__ Abn, const bf16_t* __restrict__ Bbn) {
;   const int tid = opaque_tid512(), wid = tid >> 6, lane = tid & 63, wr = wid >> 2, wc = wid & 3, fr = lane & 15, fq = lane >> 4;
;   unsigned aoff[4], boff[4];
; #pragma unroll
;   for (int i = 0; i < 4; ++i) { int R, C; stage_rc2(wid * 1024 + i * 8192 + lane * 16, R, C); aoff[i] = (unsigned)R * (unsigned)lda + (unsigned)C; boff[i] = (unsigned)R * (unsigned)ldb + (unsigned)C; }
;     ...
;   f32x4 acc[8][4];
; #pragma unroll
;   for (int m = 0; m < 8; ++m)
; #pragma unroll
;     for (int n = 0; n < 4; ++n) acc[m][n] = (f32x4){0.f, 0.f, 0.f, 0.f};
;   const int nt = K / 64;
;   if (!staged) {
;     G8_STAGE(0, Ab, Bb);
;     asm volatile("s_waitcnt vmcnt(0)" ::: "memory");
;     __syncthreads();
;   }
;   for (int t = 0; t < nt; ++t) {
;     const int cur = t & 1;
;     const unsigned char* sa = smem + cur * G8_STAGE_B;
;     const unsigned char* sb = sa + G8_TILE_B;
; #pragma unroll
;     for (int ks = 0; ks < 2; ++ks) {
;       bf16x8 At[8], Bf[4];
;       Bf[0] = *(const bf16x8*)(sb + lds_byte2(wc * 64 + fr, ks * 32 + fq * 8));
;       At[0] = *(const bf16x8*)(sa + lds_byte2(wr * 128 + fr, ks * 32 + fq * 8));
; #pragma unroll
;       for (int n = 1; n < 4; ++n) Bf[n] = *(const bf16x8*)(sb + lds_byte2(wc * 64 + n * 16 + fr, ks * 32 + fq * 8));
; #pragma unroll
;       for (int m = 1; m < 8; ++m) At[m] = *(const bf16x8*)(sa + lds_byte2(wr * 128 + m * 16 + fr, ks * 32 + fq * 8));
;       {
;         __builtin_amdgcn_sched_barrier(0);
;         if (t + 1 < nt) { G8_STAGE_R(cur ^ 1, Ab + (t + 1) * 64, Bb + (t + 1) * 64, 2 * ks, 2 * ks + 2); }
;         else if (has_next) { G8_STAGE_R(0, Abn, Bbn, 2 * ks, 2 * ks + 2); }
;         __builtin_amdgcn_sched_barrier(0);
;       }
; #pragma unroll
;       for (int m = 0; m < 8; ++m)
; #pragma unroll
;         for (int n = 0; n < 4; ++n) acc[m][n] = MFMA16(At[m], Bf[n], acc[m][n]);
.LBB0_1253:
	s_add_u32 s0, s57, s81
	s_addc_u32 s1, s58, s87
	v_lshl_add_u64 v[130:131], v[0:1], 1, s[0:1]
	v_lshl_add_u64 v[132:133], v[180:181], 1, s[0:1]
	v_lshl_add_u64 v[134:135], v[190:191], 1, s[0:1]
	v_lshl_add_u64 v[136:137], v[186:187], 1, s[0:1]
	s_lshl_b32 s0, s78, 3
	s_add_i32 s0, s28, s0
	s_add_i32 s0, s0, s79
	s_lshl_b32 s1, s75, 3
	s_sub_i32 s0, s0, s1
	v_and_b32_e32 v198, 3, v3
	v_ashrrev_i32_e32 v3, 8, v2
	v_and_b32_e32 v197, 15, v2
	v_and_b32_e32 v4, 48, v2
	v_lshlrev_b32_e32 v6, 2, v2
	v_lshlrev_b32_e32 v2, 6, v2
	s_lshl_b32 s1, s0, 8
	s_mul_i32 s0, s0, 0x88000
	v_and_b32_e32 v6, 32, v6
	v_and_b32_e32 v2, 0x3c0, v2
	s_mul_hi_i32 s1, s1, 0x880
	s_add_u32 s0, s91, s0
	v_lshlrev_b32_e32 v5, 6, v197
	v_lshlrev_b32_e32 v156, 14, v3
	v_bitop3_b32 v154, v2, v6, v4 bitop3:0x36
	s_addc_u32 s1, s72, s1
	v_lshlrev_b32_e32 v153, 13, v198
	v_bitop3_b32 v155, v5, v6, v4 bitop3:0x36
	v_lshlrev_b32_e32 v199, 7, v3
	v_or_b32_e32 v150, 0x800, v156
	v_or_b32_e32 v152, 0x1000, v156
	v_or_b32_e32 v151, 0x1800, v156
	v_or_b32_e32 v149, 0x2000, v156
	v_or_b32_e32 v148, 0x2800, v156
	v_or_b32_e32 v147, 0x3000, v156
	v_or_b32_e32 v146, 0x3800, v156
	v_lshl_add_u64 v[138:139], v[182:183], 1, s[0:1]
	v_lshl_add_u64 v[140:141], v[178:179], 1, s[0:1]
	v_lshl_add_u64 v[142:143], v[188:189], 1, s[0:1]
	v_lshl_add_u64 v[144:145], v[184:185], 1, s[0:1]
	s_mov_b64 s[0:1], 0
	s_mov_b32 s38, 0
	v_add_u32_e32 v250, 0x10000, v203
	s_nop 0
	v_readfirstlane_b32 s54, v250
	s_mov_b32 m0, s54
	v_lshl_add_u64 v[208:209], v[144:145], 0, s[0:1]
	global_load_lds_dwordx4 v[208:209], off
	s_add_u32 m0, s54, 0x8000
	v_lshl_add_u64 v[208:209], v[136:137], 0, s[0:1]
	global_load_lds_dwordx4 v[208:209], off
	s_add_u32 m0, s54, 0x2000
	v_lshl_add_u64 v[208:209], v[142:143], 0, s[0:1]
	global_load_lds_dwordx4 v[208:209], off
	s_add_u32 m0, s54, 0xa000
	v_lshl_add_u64 v[208:209], v[134:135], 0, s[0:1]
	global_load_lds_dwordx4 v[208:209], off
	s_add_u32 m0, s54, 0x4000
	v_lshl_add_u64 v[208:209], v[140:141], 0, s[0:1]
	global_load_lds_dwordx4 v[208:209], off
	s_add_u32 m0, s54, 0xc000
	v_lshl_add_u64 v[208:209], v[132:133], 0, s[0:1]
	global_load_lds_dwordx4 v[208:209], off
	s_add_u32 m0, s54, 0x6000
	v_lshl_add_u64 v[208:209], v[138:139], 0, s[0:1]
	global_load_lds_dwordx4 v[208:209], off
	s_add_u32 m0, s54, 0xe000
	v_lshl_add_u64 v[208:209], v[130:131], 0, s[0:1]
	global_load_lds_dwordx4 v[208:209], off
	s_mov_b32 s54, 0
	v_add3_u32 v157, s54, v155, v153
	v_add3_u32 v242, s54, v155, v156
	v_add3_u32 v244, s54, v154, v152
	v_add3_u32 v246, s54, v154, v149
	v_add3_u32 v248, s54, v154, v147
	v_add3_u32 v243, s54, v154, v150
	v_add3_u32 v245, s54, v154, v151
	v_add3_u32 v247, s54, v154, v148
	v_add3_u32 v249, s54, v154, v146
	ds_read_b128 v[158:161], v157 offset:32768
	ds_read_b128 v[162:165], v157 offset:34816
	ds_read_b128 v[174:177], v242
	ds_read_b128 v[204:207], v243
	ds_read_b128 v[212:215], v244
	ds_read_b128 v[222:225], v245
	ds_read_b128 v[226:229], v246
	ds_read_b128 v[230:233], v247
	ds_read_b128 v[234:237], v248
	ds_read_b128 v[238:241], v249
	ds_read_b128 v[166:169], v157 offset:36864
	ds_read_b128 v[170:173], v157 offset:38912
	s_and_b32 s39, s38, 0x10000
	s_xor_b32 s54, s39, 0x10000
	v_add_u32_e32 v250, s54, v203
	s_nop 0
	v_readfirstlane_b32 s39, v250
	s_waitcnt lgkmcnt(8)
	v_mfma_f32_16x16x32_bf16 v[126:129], v[174:177], v[158:161], 0
	v_mfma_f32_16x16x32_bf16 v[122:125], v[174:177], v[162:165], 0
	v_mfma_f32_16x16x32_bf16 v[110:113], v[204:207], v[158:161], 0
	v_mfma_f32_16x16x32_bf16 v[106:109], v[204:207], v[162:165], 0
	s_waitcnt lgkmcnt(6)
	v_mfma_f32_16x16x32_bf16 v[94:97], v[212:215], v[158:161], 0
	v_mfma_f32_16x16x32_bf16 v[90:93], v[212:215], v[162:165], 0
	v_mfma_f32_16x16x32_bf16 v[78:81], v[222:225], v[158:161], 0
	v_mfma_f32_16x16x32_bf16 v[74:77], v[222:225], v[162:165], 0
	s_waitcnt lgkmcnt(4)
	v_mfma_f32_16x16x32_bf16 v[62:65], v[226:229], v[158:161], 0
	v_mfma_f32_16x16x32_bf16 v[58:61], v[226:229], v[162:165], 0
	v_mfma_f32_16x16x32_bf16 v[46:49], v[230:233], v[158:161], 0
	v_mfma_f32_16x16x32_bf16 v[42:45], v[230:233], v[162:165], 0
	s_waitcnt lgkmcnt(2)
	v_mfma_f32_16x16x32_bf16 v[30:33], v[234:237], v[158:161], 0
	v_mfma_f32_16x16x32_bf16 v[26:29], v[234:237], v[162:165], 0
	v_mfma_f32_16x16x32_bf16 v[14:17], v[238:241], v[158:161], 0
	v_mfma_f32_16x16x32_bf16 v[10:13], v[238:241], v[162:165], 0
	ds_read_b128 v[158:161], v157 offset:33792
	ds_read_b128 v[162:165], v157 offset:35840
	s_waitcnt lgkmcnt(2)
; #define MFMA16(a, b, c) __builtin_amdgcn_mfma_f32_16x16x32_bf16((a), (b), (c), 0, 0, 0)
; template <class Epi>
; DI void gemm8_tile(const bf16_t* __restrict__ Ab, int lda, const bf16_t* __restrict__ Bb, int ldb, int K, int brow, int bcol, const Epi epi,
;                    bool staged, bool has_next, const bf16_t* __restrict__ Abn, const bf16_t* __restrict__ Bbn) {
;     ...
;   for (int t = 0; t < nt; ++t) {
;     const int cur = t & 1;
;     const unsigned char* sa = smem + cur * G8_STAGE_B;
;     const unsigned char* sb = sa + G8_TILE_B;
; #pragma unroll
;     for (int ks = 0; ks < 2; ++ks) {
;       bf16x8 At[8], Bf[4];
;       Bf[0] = *(const bf16x8*)(sb + lds_byte2(wc * 64 + fr, ks * 32 + fq * 8));
;       At[0] = *(const bf16x8*)(sa + lds_byte2(wr * 128 + fr, ks * 32 + fq * 8));
; #pragma unroll
;       for (int n = 1; n < 4; ++n) Bf[n] = *(const bf16x8*)(sb + lds_byte2(wc * 64 + n * 16 + fr, ks * 32 + fq * 8));
; #pragma unroll
;       for (int m = 1; m < 8; ++m) At[m] = *(const bf16x8*)(sa + lds_byte2(wr * 128 + m * 16 + fr, ks * 32 + fq * 8));
;       {
;         __builtin_amdgcn_sched_barrier(0);
;         if (t + 1 < nt) { G8_STAGE_R(cur ^ 1, Ab + (t + 1) * 64, Bb + (t + 1) * 64, 2 * ks, 2 * ks + 2); }
;         else if (has_next) { G8_STAGE_R(0, Abn, Bbn, 2 * ks, 2 * ks + 2); }
;         __builtin_amdgcn_sched_barrier(0);
;       }
; #pragma unroll
;       for (int m = 0; m < 8; ++m)
; #pragma unroll
;         for (int n = 0; n < 4; ++n) acc[m][n] = MFMA16(At[m], Bf[n], acc[m][n]);
;       __builtin_amdgcn_sched_barrier(0);
;     }
;     asm volatile("s_waitcnt vmcnt(0)" ::: "memory");
;     __syncthreads();
	v_mfma_f32_16x16x32_bf16 v[118:121], v[174:177], v[166:169], 0
	v_mfma_f32_16x16x32_bf16 v[114:117], v[174:177], v[170:173], 0
	ds_read_b128 v[174:177], v242 offset:1024
	v_mfma_f32_16x16x32_bf16 v[102:105], v[204:207], v[166:169], 0
	v_mfma_f32_16x16x32_bf16 v[98:101], v[204:207], v[170:173], 0
	ds_read_b128 v[204:207], v243 offset:1024
	v_mfma_f32_16x16x32_bf16 v[86:89], v[212:215], v[166:169], 0
	v_mfma_f32_16x16x32_bf16 v[82:85], v[212:215], v[170:173], 0
	ds_read_b128 v[212:215], v244 offset:1024
	v_mfma_f32_16x16x32_bf16 v[70:73], v[222:225], v[166:169], 0
	v_mfma_f32_16x16x32_bf16 v[66:69], v[222:225], v[170:173], 0
	ds_read_b128 v[222:225], v245 offset:1024
	v_mfma_f32_16x16x32_bf16 v[54:57], v[226:229], v[166:169], 0
	v_mfma_f32_16x16x32_bf16 v[50:53], v[226:229], v[170:173], 0
	ds_read_b128 v[226:229], v246 offset:1024
	v_mfma_f32_16x16x32_bf16 v[38:41], v[230:233], v[166:169], 0
	v_mfma_f32_16x16x32_bf16 v[34:37], v[230:233], v[170:173], 0
	ds_read_b128 v[230:233], v247 offset:1024
	v_mfma_f32_16x16x32_bf16 v[22:25], v[234:237], v[166:169], 0
	v_mfma_f32_16x16x32_bf16 v[18:21], v[234:237], v[170:173], 0
	ds_read_b128 v[234:237], v248 offset:1024
	v_mfma_f32_16x16x32_bf16 v[6:9], v[238:241], v[166:169], 0
	v_mfma_f32_16x16x32_bf16 v[2:5], v[238:241], v[170:173], 0
	ds_read_b128 v[238:241], v249 offset:1024
	ds_read_b128 v[166:169], v157 offset:37888
	ds_read_b128 v[170:173], v157 offset:39936
	s_waitcnt lgkmcnt(8)
	v_mfma_f32_16x16x32_bf16 v[126:129], v[174:177], v[158:161], v[126:129]
	v_mfma_f32_16x16x32_bf16 v[122:125], v[174:177], v[162:165], v[122:125]
	v_add3_u32 v157, s54, v155, v153
	v_mfma_f32_16x16x32_bf16 v[110:113], v[204:207], v[158:161], v[110:113]
	v_mfma_f32_16x16x32_bf16 v[106:109], v[204:207], v[162:165], v[106:109]
	v_add3_u32 v242, s54, v155, v156
	s_waitcnt lgkmcnt(6)
	v_mfma_f32_16x16x32_bf16 v[94:97], v[212:215], v[158:161], v[94:97]
	v_mfma_f32_16x16x32_bf16 v[90:93], v[212:215], v[162:165], v[90:93]
	v_add3_u32 v244, s54, v154, v152
	v_mfma_f32_16x16x32_bf16 v[78:81], v[222:225], v[158:161], v[78:81]
	v_mfma_f32_16x16x32_bf16 v[74:77], v[222:225], v[162:165], v[74:77]
	v_add3_u32 v246, s54, v154, v149
	s_waitcnt lgkmcnt(4)
	v_mfma_f32_16x16x32_bf16 v[62:65], v[226:229], v[158:161], v[62:65]
	v_mfma_f32_16x16x32_bf16 v[58:61], v[226:229], v[162:165], v[58:61]
	v_add3_u32 v248, s54, v154, v147
	v_mfma_f32_16x16x32_bf16 v[46:49], v[230:233], v[158:161], v[46:49]
	v_mfma_f32_16x16x32_bf16 v[42:45], v[230:233], v[162:165], v[42:45]
	v_add3_u32 v243, s54, v154, v150
	s_waitcnt lgkmcnt(2)
	v_mfma_f32_16x16x32_bf16 v[30:33], v[234:237], v[158:161], v[30:33]
	v_mfma_f32_16x16x32_bf16 v[26:29], v[234:237], v[162:165], v[26:29]
	v_add3_u32 v245, s54, v154, v151
	v_mfma_f32_16x16x32_bf16 v[14:17], v[238:241], v[158:161], v[14:17]
	v_mfma_f32_16x16x32_bf16 v[10:13], v[238:241], v[162:165], v[10:13]
	v_add3_u32 v247, s54, v154, v148
	v_add3_u32 v249, s54, v154, v146
	s_waitcnt vmcnt(0) lgkmcnt(0)
	s_barrier
	s_add_u32 s0, s0, 0x80
	s_addc_u32 s1, s1, 0
	s_add_i32 s38, s38, 0x10000
	s_xor_b32 s54, s39, 0x10000
	ds_read_b128 v[158:161], v157 offset:32768
	ds_read_b128 v[162:165], v157 offset:34816
	v_mfma_f32_16x16x32_bf16 v[118:121], v[174:177], v[166:169], v[118:121]
	v_mfma_f32_16x16x32_bf16 v[114:117], v[174:177], v[170:173], v[114:117]
	ds_read_b128 v[174:177], v242
	s_mov_b32 m0, s54
	v_lshl_add_u64 v[208:209], v[144:145], 0, s[0:1]
	global_load_lds_dwordx4 v[208:209], off
	v_mfma_f32_16x16x32_bf16 v[102:105], v[204:207], v[166:169], v[102:105]
	v_mfma_f32_16x16x32_bf16 v[98:101], v[204:207], v[170:173], v[98:101]
	ds_read_b128 v[204:207], v243
	s_add_u32 m0, s54, 0x8000
	v_lshl_add_u64 v[208:209], v[136:137], 0, s[0:1]
	global_load_lds_dwordx4 v[208:209], off
	v_mfma_f32_16x16x32_bf16 v[86:89], v[212:215], v[166:169], v[86:89]
	v_mfma_f32_16x16x32_bf16 v[82:85], v[212:215], v[170:173], v[82:85]
	ds_read_b128 v[212:215], v244
	s_add_u32 m0, s54, 0x2000
	v_lshl_add_u64 v[208:209], v[142:143], 0, s[0:1]
	global_load_lds_dwordx4 v[208:209], off
	v_mfma_f32_16x16x32_bf16 v[70:73], v[222:225], v[166:169], v[70:73]
	v_mfma_f32_16x16x32_bf16 v[66:69], v[222:225], v[170:173], v[66:69]
	ds_read_b128 v[222:225], v245
	s_add_u32 m0, s54, 0xa000
	v_lshl_add_u64 v[208:209], v[134:135], 0, s[0:1]
	global_load_lds_dwordx4 v[208:209], off
	v_mfma_f32_16x16x32_bf16 v[54:57], v[226:229], v[166:169], v[54:57]
	v_mfma_f32_16x16x32_bf16 v[50:53], v[226:229], v[170:173], v[50:53]
	ds_read_b128 v[226:229], v246
	s_add_u32 m0, s54, 0x4000
	v_lshl_add_u64 v[208:209], v[140:141], 0, s[0:1]
	global_load_lds_dwordx4 v[208:209], off
	v_mfma_f32_16x16x32_bf16 v[38:41], v[230:233], v[166:169], v[38:41]
	v_mfma_f32_16x16x32_bf16 v[34:37], v[230:233], v[170:173], v[34:37]
	ds_read_b128 v[230:233], v247
	s_add_u32 m0, s54, 0xc000
	v_lshl_add_u64 v[208:209], v[132:133], 0, s[0:1]
	global_load_lds_dwordx4 v[208:209], off
	v_mfma_f32_16x16x32_bf16 v[22:25], v[234:237], v[166:169], v[22:25]
	v_mfma_f32_16x16x32_bf16 v[18:21], v[234:237], v[170:173], v[18:21]
	ds_read_b128 v[234:237], v248
	s_add_u32 m0, s54, 0x6000
	v_lshl_add_u64 v[208:209], v[138:139], 0, s[0:1]
	global_load_lds_dwordx4 v[208:209], off
	v_mfma_f32_16x16x32_bf16 v[6:9], v[238:241], v[166:169], v[6:9]
	v_mfma_f32_16x16x32_bf16 v[2:5], v[238:241], v[170:173], v[2:5]
	ds_read_b128 v[238:241], v249
	s_add_u32 m0, s54, 0xe000
	v_lshl_add_u64 v[208:209], v[130:131], 0, s[0:1]
	global_load_lds_dwordx4 v[208:209], off
	ds_read_b128 v[166:169], v157 offset:36864
	ds_read_b128 v[170:173], v157 offset:38912

; DI int opaque_tid512() { int t = threadIdx.x; asm volatile("" : "+v"(t)); return t; }
; #define MFMA16(a, b, c) __builtin_amdgcn_mfma_f32_16x16x32_bf16((a), (b), (c), 0, 0, 0)
; #define G8_STAGE(buf_, ap_, bp_) G8_STAGE_R(buf_, ap_, bp_, 0, 4)
; template <class Epi>
; DI void gemm8_tile(const bf16_t* __restrict__ Ab, int lda, const bf16_t* __restrict__ Bb, int ldb, int K, int brow, int bcol, const Epi epi,
;                    bool staged, bool has_next, const bf16_t* __restrict__ Abn, const bf16_t* __restrict__ Bbn) {
;   const int tid = opaque_tid512(), wid = tid >> 6, lane = tid & 63, wr = wid >> 2, wc = wid & 3, fr = lane & 15, fq = lane >> 4;
;   unsigned aoff[4], boff[4];
; #pragma unroll
;   for (int i = 0; i < 4; ++i) { int R, C; stage_rc2(wid * 1024 + i * 8192 + lane * 16, R, C); aoff[i] = (unsigned)R * (unsigned)lda + (unsigned)C; boff[i] = (unsigned)R * (unsigned)ldb + (unsigned)C; }
;     ...
;   f32x4 acc[8][4];
; #pragma unroll
;   for (int m = 0; m < 8; ++m)
; #pragma unroll
;     for (int n = 0; n < 4; ++n) acc[m][n] = (f32x4){0.f, 0.f, 0.f, 0.f};
;   const int nt = K / 64;
;   if (!staged) {
;     G8_STAGE(0, Ab, Bb);
;     asm volatile("s_waitcnt vmcnt(0)" ::: "memory");
;     __syncthreads();
;   }
;   for (int t = 0; t < nt; ++t) {
;     const int cur = t & 1;
;     const unsigned char* sa = smem + cur * G8_STAGE_B;
;     const unsigned char* sb = sa + G8_TILE_B;
; #pragma unroll
;     for (int ks = 0; ks < 2; ++ks) {
;       bf16x8 At[8], Bf[4];
;       Bf[0] = *(const bf16x8*)(sb + lds_byte2(wc * 64 + fr, ks * 32 + fq * 8));
;       At[0] = *(const bf16x8*)(sa + lds_byte2(wr * 128 + fr, ks * 32 + fq * 8));
; #pragma unroll
;       for (int n = 1; n < 4; ++n) Bf[n] = *(const bf16x8*)(sb + lds_byte2(wc * 64 + n * 16 + fr, ks * 32 + fq * 8));
; #pragma unroll
;       for (int m = 1; m < 8; ++m) At[m] = *(const bf16x8*)(sa + lds_byte2(wr * 128 + m * 16 + fr, ks * 32 + fq * 8));
;       {
;         __builtin_amdgcn_sched_barrier(0);
;         if (t + 1 < nt) { G8_STAGE_R(cur ^ 1, Ab + (t + 1) * 64, Bb + (t + 1) * 64, 2 * ks, 2 * ks + 2); }
;         else if (has_next) { G8_STAGE_R(0, Abn, Bbn, 2 * ks, 2 * ks + 2); }
;         __builtin_amdgcn_sched_barrier(0);
;       }
; #pragma unroll
;       for (int m = 0; m < 8; ++m)
; #pragma unroll
;         for (int n = 0; n < 4; ++n) acc[m][n] = MFMA16(At[m], Bf[n], acc[m][n]);
.LBB0_1311:
	s_lshl_b32 s0, s74, 3
	s_add_i32 s0, s28, s0
	s_add_i32 s0, s0, s75
	s_lshl_b32 s1, s71, 3
	s_sub_i32 s0, s0, s1
	s_lshl_b32 s1, s0, 8
	s_mul_i32 s0, s0, 0x88000
	s_mul_hi_i32 s1, s1, 0x880
	s_add_u32 s0, s91, s0
	v_and_b32_e32 v198, 15, v8
	v_lshlrev_b64 v[178:179], 1, v[4:5]
	s_addc_u32 s1, s72, s1
	v_lshlrev_b64 v[180:181], 1, v[2:3]
	v_lshlrev_b64 v[194:195], 1, v[6:7]
	v_lshlrev_b64 v[196:197], 1, v[0:1]
	v_and_b32_e32 v206, 63, v8
	v_ashrrev_i32_e32 v10, 8, v8
	v_and_b32_e32 v204, 3, v9
	v_and_b32_e32 v9, 48, v8
	v_lshlrev_b32_e32 v199, 2, v198
	v_lshlrev_b32_e32 v8, 6, v8
	v_lshl_add_u64 v[130:131], s[0:1], 0, v[178:179]
	v_lshl_add_u64 v[132:133], s[0:1], 0, v[180:181]
	v_lshl_add_u64 v[134:135], s[0:1], 0, v[194:195]
	v_lshl_add_u64 v[136:137], s[0:1], 0, v[196:197]
	s_add_u32 s0, s57, s78
	v_lshlrev_b32_e32 v11, 6, v198
	v_and_b32_e32 v12, 32, v199
	v_lshlrev_b32_e32 v156, 14, v10
	v_and_b32_e32 v8, 0x3c0, v8
	s_addc_u32 s1, s58, s79
	v_lshlrev_b32_e32 v153, 13, v204
	v_bitop3_b32 v155, v11, v12, v9 bitop3:0x36
	v_lshlrev_b32_e32 v205, 7, v10
	v_or_b32_e32 v150, 0x800, v156
	v_bitop3_b32 v154, v8, v12, v9 bitop3:0x36
	v_or_b32_e32 v152, 0x1000, v156
	v_or_b32_e32 v151, 0x1800, v156
	v_or_b32_e32 v149, 0x2000, v156
	v_or_b32_e32 v148, 0x2800, v156
	v_or_b32_e32 v147, 0x3000, v156
	v_or_b32_e32 v146, 0x3800, v156
	v_lshl_add_u64 v[138:139], s[0:1], 0, v[178:179]
	v_lshl_add_u64 v[140:141], s[0:1], 0, v[180:181]
	v_lshl_add_u64 v[142:143], s[0:1], 0, v[194:195]
	v_lshl_add_u64 v[144:145], s[0:1], 0, v[196:197]
	s_mov_b64 s[0:1], 0
	s_mov_b32 s38, 0
	v_add_u32_e32 v244, 0x10000, v185
	s_nop 0
	v_readfirstlane_b32 s54, v244
	s_mov_b32 m0, s54
	v_lshl_add_u64 v[208:209], v[130:131], 0, s[0:1]
	global_load_lds_dwordx4 v[208:209], off
	s_add_u32 m0, s54, 0x8000
	v_lshl_add_u64 v[208:209], v[138:139], 0, s[0:1]
	global_load_lds_dwordx4 v[208:209], off
	s_add_u32 m0, s54, 0x2000
	v_lshl_add_u64 v[208:209], v[132:133], 0, s[0:1]
	global_load_lds_dwordx4 v[208:209], off
	s_add_u32 m0, s54, 0xa000
	v_lshl_add_u64 v[208:209], v[140:141], 0, s[0:1]
	global_load_lds_dwordx4 v[208:209], off
	s_add_u32 m0, s54, 0x4000
	v_lshl_add_u64 v[208:209], v[134:135], 0, s[0:1]
	global_load_lds_dwordx4 v[208:209], off
	s_add_u32 m0, s54, 0xc000
	v_lshl_add_u64 v[208:209], v[142:143], 0, s[0:1]
	global_load_lds_dwordx4 v[208:209], off
	s_add_u32 m0, s54, 0x6000
	v_lshl_add_u64 v[208:209], v[136:137], 0, s[0:1]
	global_load_lds_dwordx4 v[208:209], off
	s_add_u32 m0, s54, 0xe000
	v_lshl_add_u64 v[208:209], v[144:145], 0, s[0:1]
	global_load_lds_dwordx4 v[208:209], off
	s_mov_b32 s54, 0
	v_add3_u32 v0, s54, v155, v153
	v_add3_u32 v157, s54, v155, v156
	v_add3_u32 v238, s54, v154, v152
	v_add3_u32 v240, s54, v154, v149
	v_add3_u32 v242, s54, v154, v147
	v_add3_u32 v207, s54, v154, v150
	v_add3_u32 v239, s54, v154, v151
	v_add3_u32 v241, s54, v154, v148
	v_add3_u32 v243, s54, v154, v146
	ds_read_b128 v[158:161], v0 offset:32768
	ds_read_b128 v[162:165], v0 offset:34816
	ds_read_b128 v[174:177], v157
	ds_read_b128 v[186:189], v207
	ds_read_b128 v[190:193], v238
	ds_read_b128 v[212:215], v239
	ds_read_b128 v[222:225], v240
	ds_read_b128 v[226:229], v241
	ds_read_b128 v[230:233], v242
	ds_read_b128 v[234:237], v243
	ds_read_b128 v[166:169], v0 offset:36864
	ds_read_b128 v[170:173], v0 offset:38912
	s_and_b32 s39, s38, 0x10000
	s_xor_b32 s54, s39, 0x10000
	v_add_u32_e32 v244, s54, v185
	s_nop 0
	v_readfirstlane_b32 s39, v244
	s_waitcnt lgkmcnt(8)
	v_mfma_f32_16x16x32_bf16 v[126:129], v[174:177], v[158:161], 0
	v_mfma_f32_16x16x32_bf16 v[122:125], v[174:177], v[162:165], 0
	v_mfma_f32_16x16x32_bf16 v[110:113], v[186:189], v[158:161], 0
	v_mfma_f32_16x16x32_bf16 v[106:109], v[186:189], v[162:165], 0
	s_waitcnt lgkmcnt(6)
	v_mfma_f32_16x16x32_bf16 v[94:97], v[190:193], v[158:161], 0
	v_mfma_f32_16x16x32_bf16 v[90:93], v[190:193], v[162:165], 0
	v_mfma_f32_16x16x32_bf16 v[78:81], v[212:215], v[158:161], 0
	v_mfma_f32_16x16x32_bf16 v[74:77], v[212:215], v[162:165], 0
	s_waitcnt lgkmcnt(4)
	v_mfma_f32_16x16x32_bf16 v[62:65], v[222:225], v[158:161], 0
	v_mfma_f32_16x16x32_bf16 v[58:61], v[222:225], v[162:165], 0
	v_mfma_f32_16x16x32_bf16 v[46:49], v[226:229], v[158:161], 0
	v_mfma_f32_16x16x32_bf16 v[42:45], v[226:229], v[162:165], 0
	s_waitcnt lgkmcnt(2)
	v_mfma_f32_16x16x32_bf16 v[30:33], v[230:233], v[158:161], 0
	v_mfma_f32_16x16x32_bf16 v[26:29], v[230:233], v[162:165], 0
	v_mfma_f32_16x16x32_bf16 v[14:17], v[234:237], v[158:161], 0
	v_mfma_f32_16x16x32_bf16 v[10:13], v[234:237], v[162:165], 0
	ds_read_b128 v[158:161], v0 offset:33792
	ds_read_b128 v[162:165], v0 offset:35840
	s_waitcnt lgkmcnt(2)
; #define MFMA16(a, b, c) __builtin_amdgcn_mfma_f32_16x16x32_bf16((a), (b), (c), 0, 0, 0)
; template <class Epi>
; DI void gemm8_tile(const bf16_t* __restrict__ Ab, int lda, const bf16_t* __restrict__ Bb, int ldb, int K, int brow, int bcol, const Epi epi,
;                    bool staged, bool has_next, const bf16_t* __restrict__ Abn, const bf16_t* __restrict__ Bbn) {
;     ...
;   for (int t = 0; t < nt; ++t) {
;     const int cur = t & 1;
;     const unsigned char* sa = smem + cur * G8_STAGE_B;
;     const unsigned char* sb = sa + G8_TILE_B;
; #pragma unroll
;     for (int ks = 0; ks < 2; ++ks) {
;       bf16x8 At[8], Bf[4];
;       Bf[0] = *(const bf16x8*)(sb + lds_byte2(wc * 64 + fr, ks * 32 + fq * 8));
;       At[0] = *(const bf16x8*)(sa + lds_byte2(wr * 128 + fr, ks * 32 + fq * 8));
; #pragma unroll
;       for (int n = 1; n < 4; ++n) Bf[n] = *(const bf16x8*)(sb + lds_byte2(wc * 64 + n * 16 + fr, ks * 32 + fq * 8));
; #pragma unroll
;       for (int m = 1; m < 8; ++m) At[m] = *(const bf16x8*)(sa + lds_byte2(wr * 128 + m * 16 + fr, ks * 32 + fq * 8));
;       {
;         __builtin_amdgcn_sched_barrier(0);
;         if (t + 1 < nt) { G8_STAGE_R(cur ^ 1, Ab + (t + 1) * 64, Bb + (t + 1) * 64, 2 * ks, 2 * ks + 2); }
;         else if (has_next) { G8_STAGE_R(0, Abn, Bbn, 2 * ks, 2 * ks + 2); }
;         __builtin_amdgcn_sched_barrier(0);
;       }
; #pragma unroll
;       for (int m = 0; m < 8; ++m)
; #pragma unroll
;         for (int n = 0; n < 4; ++n) acc[m][n] = MFMA16(At[m], Bf[n], acc[m][n]);
;       __builtin_amdgcn_sched_barrier(0);
;     }
;     asm volatile("s_waitcnt vmcnt(0)" ::: "memory");
;     __syncthreads();
	v_mfma_f32_16x16x32_bf16 v[118:121], v[174:177], v[166:169], 0
	v_mfma_f32_16x16x32_bf16 v[114:117], v[174:177], v[170:173], 0
	ds_read_b128 v[174:177], v157 offset:1024
	v_mfma_f32_16x16x32_bf16 v[102:105], v[186:189], v[166:169], 0
	v_mfma_f32_16x16x32_bf16 v[98:101], v[186:189], v[170:173], 0
	ds_read_b128 v[186:189], v207 offset:1024
	v_mfma_f32_16x16x32_bf16 v[86:89], v[190:193], v[166:169], 0
	v_mfma_f32_16x16x32_bf16 v[82:85], v[190:193], v[170:173], 0
	ds_read_b128 v[190:193], v238 offset:1024
	v_mfma_f32_16x16x32_bf16 v[70:73], v[212:215], v[166:169], 0
	v_mfma_f32_16x16x32_bf16 v[66:69], v[212:215], v[170:173], 0
	ds_read_b128 v[212:215], v239 offset:1024
	v_mfma_f32_16x16x32_bf16 v[54:57], v[222:225], v[166:169], 0
	v_mfma_f32_16x16x32_bf16 v[50:53], v[222:225], v[170:173], 0
	ds_read_b128 v[222:225], v240 offset:1024
	v_mfma_f32_16x16x32_bf16 v[38:41], v[226:229], v[166:169], 0
	v_mfma_f32_16x16x32_bf16 v[34:37], v[226:229], v[170:173], 0
	ds_read_b128 v[226:229], v241 offset:1024
	v_mfma_f32_16x16x32_bf16 v[22:25], v[230:233], v[166:169], 0
	v_mfma_f32_16x16x32_bf16 v[18:21], v[230:233], v[170:173], 0
	ds_read_b128 v[230:233], v242 offset:1024
	v_mfma_f32_16x16x32_bf16 v[6:9], v[234:237], v[166:169], 0
	v_mfma_f32_16x16x32_bf16 v[2:5], v[234:237], v[170:173], 0
	ds_read_b128 v[234:237], v243 offset:1024
	ds_read_b128 v[166:169], v0 offset:37888
	ds_read_b128 v[170:173], v0 offset:39936
	s_waitcnt lgkmcnt(8)
	v_mfma_f32_16x16x32_bf16 v[126:129], v[174:177], v[158:161], v[126:129]
	v_mfma_f32_16x16x32_bf16 v[122:125], v[174:177], v[162:165], v[122:125]
	v_add3_u32 v0, s54, v155, v153
	v_mfma_f32_16x16x32_bf16 v[110:113], v[186:189], v[158:161], v[110:113]
	v_mfma_f32_16x16x32_bf16 v[106:109], v[186:189], v[162:165], v[106:109]
	v_add3_u32 v157, s54, v155, v156
	s_waitcnt lgkmcnt(6)
	v_mfma_f32_16x16x32_bf16 v[94:97], v[190:193], v[158:161], v[94:97]
	v_mfma_f32_16x16x32_bf16 v[90:93], v[190:193], v[162:165], v[90:93]
	v_add3_u32 v238, s54, v154, v152
	v_mfma_f32_16x16x32_bf16 v[78:81], v[212:215], v[158:161], v[78:81]
	v_mfma_f32_16x16x32_bf16 v[74:77], v[212:215], v[162:165], v[74:77]
	v_add3_u32 v240, s54, v154, v149
	s_waitcnt lgkmcnt(4)
	v_mfma_f32_16x16x32_bf16 v[62:65], v[222:225], v[158:161], v[62:65]
	v_mfma_f32_16x16x32_bf16 v[58:61], v[222:225], v[162:165], v[58:61]
	v_add3_u32 v242, s54, v154, v147
	v_mfma_f32_16x16x32_bf16 v[46:49], v[226:229], v[158:161], v[46:49]
	v_mfma_f32_16x16x32_bf16 v[42:45], v[226:229], v[162:165], v[42:45]
	v_add3_u32 v207, s54, v154, v150
	s_waitcnt lgkmcnt(2)
	v_mfma_f32_16x16x32_bf16 v[30:33], v[230:233], v[158:161], v[30:33]
	v_mfma_f32_16x16x32_bf16 v[26:29], v[230:233], v[162:165], v[26:29]
	v_add3_u32 v239, s54, v154, v151
	v_mfma_f32_16x16x32_bf16 v[14:17], v[234:237], v[158:161], v[14:17]
	v_mfma_f32_16x16x32_bf16 v[10:13], v[234:237], v[162:165], v[10:13]
	v_add3_u32 v241, s54, v154, v148
	v_add3_u32 v243, s54, v154, v146
	s_waitcnt vmcnt(0) lgkmcnt(0)
	s_barrier
	s_add_u32 s0, s0, 0x80
	s_addc_u32 s1, s1, 0
	s_add_i32 s38, s38, 0x10000
	s_xor_b32 s54, s39, 0x10000
	ds_read_b128 v[158:161], v0 offset:32768
	ds_read_b128 v[162:165], v0 offset:34816
	v_mfma_f32_16x16x32_bf16 v[118:121], v[174:177], v[166:169], v[118:121]
	v_mfma_f32_16x16x32_bf16 v[114:117], v[174:177], v[170:173], v[114:117]
	ds_read_b128 v[174:177], v157
	s_mov_b32 m0, s54
	v_lshl_add_u64 v[208:209], v[130:131], 0, s[0:1]
	global_load_lds_dwordx4 v[208:209], off
	v_mfma_f32_16x16x32_bf16 v[102:105], v[186:189], v[166:169], v[102:105]
	v_mfma_f32_16x16x32_bf16 v[98:101], v[186:189], v[170:173], v[98:101]
	ds_read_b128 v[186:189], v207
	s_add_u32 m0, s54, 0x8000
	v_lshl_add_u64 v[208:209], v[138:139], 0, s[0:1]
	global_load_lds_dwordx4 v[208:209], off
	v_mfma_f32_16x16x32_bf16 v[86:89], v[190:193], v[166:169], v[86:89]
	v_mfma_f32_16x16x32_bf16 v[82:85], v[190:193], v[170:173], v[82:85]
	ds_read_b128 v[190:193], v238
	s_add_u32 m0, s54, 0x2000
	v_lshl_add_u64 v[208:209], v[132:133], 0, s[0:1]
	global_load_lds_dwordx4 v[208:209], off
	v_mfma_f32_16x16x32_bf16 v[70:73], v[212:215], v[166:169], v[70:73]
	v_mfma_f32_16x16x32_bf16 v[66:69], v[212:215], v[170:173], v[66:69]
	ds_read_b128 v[212:215], v239
	s_add_u32 m0, s54, 0xa000
	v_lshl_add_u64 v[208:209], v[140:141], 0, s[0:1]
	global_load_lds_dwordx4 v[208:209], off
	v_mfma_f32_16x16x32_bf16 v[54:57], v[222:225], v[166:169], v[54:57]
	v_mfma_f32_16x16x32_bf16 v[50:53], v[222:225], v[170:173], v[50:53]
	ds_read_b128 v[222:225], v240
	s_add_u32 m0, s54, 0x4000
	v_lshl_add_u64 v[208:209], v[134:135], 0, s[0:1]
	global_load_lds_dwordx4 v[208:209], off
	v_mfma_f32_16x16x32_bf16 v[38:41], v[226:229], v[166:169], v[38:41]
	v_mfma_f32_16x16x32_bf16 v[34:37], v[226:229], v[170:173], v[34:37]
	ds_read_b128 v[226:229], v241
	s_add_u32 m0, s54, 0xc000
	v_lshl_add_u64 v[208:209], v[142:143], 0, s[0:1]
	global_load_lds_dwordx4 v[208:209], off
	v_mfma_f32_16x16x32_bf16 v[22:25], v[230:233], v[166:169], v[22:25]
	v_mfma_f32_16x16x32_bf16 v[18:21], v[230:233], v[170:173], v[18:21]
	ds_read_b128 v[230:233], v242
	s_add_u32 m0, s54, 0x6000
	v_lshl_add_u64 v[208:209], v[136:137], 0, s[0:1]
	global_load_lds_dwordx4 v[208:209], off
	v_mfma_f32_16x16x32_bf16 v[6:9], v[234:237], v[166:169], v[6:9]
	v_mfma_f32_16x16x32_bf16 v[2:5], v[234:237], v[170:173], v[2:5]
	ds_read_b128 v[234:237], v243
	s_add_u32 m0, s54, 0xe000
	v_lshl_add_u64 v[208:209], v[144:145], 0, s[0:1]
	global_load_lds_dwordx4 v[208:209], off
	ds_read_b128 v[166:169], v0 offset:36864
	ds_read_b128 v[170:173], v0 offset:38912

; DI int opaque_tid512() { int t = threadIdx.x; asm volatile("" : "+v"(t)); return t; }
; #define MFMA16(a, b, c) __builtin_amdgcn_mfma_f32_16x16x32_bf16((a), (b), (c), 0, 0, 0)
; #define G8_STAGE(buf_, ap_, bp_) G8_STAGE_R(buf_, ap_, bp_, 0, 4)
; template <class Epi>
; DI void gemm8_tile(const bf16_t* __restrict__ Ab, int lda, const bf16_t* __restrict__ Bb, int ldb, int K, int brow, int bcol, const Epi epi,
;                    bool staged, bool has_next, const bf16_t* __restrict__ Abn, const bf16_t* __restrict__ Bbn) {
;   const int tid = opaque_tid512(), wid = tid >> 6, lane = tid & 63, wr = wid >> 2, wc = wid & 3, fr = lane & 15, fq = lane >> 4;
;   unsigned aoff[4], boff[4];
; #pragma unroll
;   for (int i = 0; i < 4; ++i) { int R, C; stage_rc2(wid * 1024 + i * 8192 + lane * 16, R, C); aoff[i] = (unsigned)R * (unsigned)lda + (unsigned)C; boff[i] = (unsigned)R * (unsigned)ldb + (unsigned)C; }
;     ...
;   f32x4 acc[8][4];
; #pragma unroll
;   for (int m = 0; m < 8; ++m)
; #pragma unroll
;     for (int n = 0; n < 4; ++n) acc[m][n] = (f32x4){0.f, 0.f, 0.f, 0.f};
;   const int nt = K / 64;
;   if (!staged) {
;     G8_STAGE(0, Ab, Bb);
;     asm volatile("s_waitcnt vmcnt(0)" ::: "memory");
;     __syncthreads();
;   }
;   for (int t = 0; t < nt; ++t) {
;     const int cur = t & 1;
;     const unsigned char* sa = smem + cur * G8_STAGE_B;
;     const unsigned char* sb = sa + G8_TILE_B;
; #pragma unroll
;     for (int ks = 0; ks < 2; ++ks) {
;       bf16x8 At[8], Bf[4];
;       Bf[0] = *(const bf16x8*)(sb + lds_byte2(wc * 64 + fr, ks * 32 + fq * 8));
;       At[0] = *(const bf16x8*)(sa + lds_byte2(wr * 128 + fr, ks * 32 + fq * 8));
; #pragma unroll
;       for (int n = 1; n < 4; ++n) Bf[n] = *(const bf16x8*)(sb + lds_byte2(wc * 64 + n * 16 + fr, ks * 32 + fq * 8));
; #pragma unroll
;       for (int m = 1; m < 8; ++m) At[m] = *(const bf16x8*)(sa + lds_byte2(wr * 128 + m * 16 + fr, ks * 32 + fq * 8));
;       {
;         __builtin_amdgcn_sched_barrier(0);
;         if (t + 1 < nt) { G8_STAGE_R(cur ^ 1, Ab + (t + 1) * 64, Bb + (t + 1) * 64, 2 * ks, 2 * ks + 2); }
;         else if (has_next) { G8_STAGE_R(0, Abn, Bbn, 2 * ks, 2 * ks + 2); }
;         __builtin_amdgcn_sched_barrier(0);
;       }
; #pragma unroll
;       for (int m = 0; m < 8; ++m)
; #pragma unroll
;         for (int n = 0; n < 4; ++n) acc[m][n] = MFMA16(At[m], Bf[n], acc[m][n]);
.LBB0_1509:
	s_lshl_b32 s14, s75, 3
	s_add_i32 s14, s28, s14
	s_add_i32 s14, s14, s78
	s_lshl_b32 s15, s74, 3
	s_sub_i32 s14, s14, s15
	s_lshl_b32 s15, s14, 8
	s_add_u32 s0, s91, s0
	s_mul_i32 s14, s14, 0x88000
	s_addc_u32 s1, s72, s1
	v_and_b32_e32 v200, 15, v2
	s_mul_hi_i32 s15, s15, 0x880
	s_add_u32 s0, s0, s14
	v_and_b32_e32 v208, 63, v2
	v_ashrrev_i32_e32 v4, 8, v2
	v_and_b32_e32 v206, 3, v3
	v_and_b32_e32 v3, 48, v2
	v_lshlrev_b32_e32 v201, 2, v200
	v_lshlrev_b32_e32 v2, 6, v2
	s_addc_u32 s1, s1, s15
	v_and_b32_e32 v6, 32, v201
	v_and_b32_e32 v2, 0x3c0, v2
	v_lshl_add_u64 v[130:131], v[178:179], 1, s[0:1]
	v_lshl_add_u64 v[132:133], v[182:183], 1, s[0:1]
	v_lshl_add_u64 v[134:135], v[194:195], 1, s[0:1]
	v_lshl_add_u64 v[136:137], v[198:199], 1, s[0:1]
	s_add_u32 s0, s59, s9
	v_lshlrev_b32_e32 v5, 6, v200
	v_lshlrev_b32_e32 v156, 14, v4
	v_bitop3_b32 v154, v2, v6, v3 bitop3:0x36
	s_addc_u32 s1, s70, s79
	v_lshlrev_b32_e32 v153, 13, v206
	v_bitop3_b32 v155, v5, v6, v3 bitop3:0x36
	v_lshlrev_b32_e32 v207, 7, v4
	v_or_b32_e32 v150, 0x800, v156
	v_or_b32_e32 v152, 0x1000, v156
	v_or_b32_e32 v151, 0x1800, v156
	v_or_b32_e32 v149, 0x2000, v156
	v_or_b32_e32 v148, 0x2800, v156
	v_or_b32_e32 v147, 0x3000, v156
	v_or_b32_e32 v146, 0x3800, v156
	v_lshl_add_u64 v[138:139], v[180:181], 1, s[0:1]
	v_lshl_add_u64 v[140:141], v[184:185], 1, s[0:1]
	v_lshl_add_u64 v[142:143], v[196:197], 1, s[0:1]
	v_lshl_add_u64 v[144:145], v[0:1], 1, s[0:1]
	s_mov_b64 s[0:1], 0
	s_mov_b32 s9, 0
	v_add_u32_e32 v251, 0x10000, v189
	s_nop 0
	v_readfirstlane_b32 s15, v251
	s_mov_b32 m0, s15
	v_lshl_add_u64 v[242:243], v[130:131], 0, s[0:1]
	global_load_lds_dwordx4 v[242:243], off
	s_add_u32 m0, s15, 0x8000
	v_lshl_add_u64 v[242:243], v[138:139], 0, s[0:1]
	global_load_lds_dwordx4 v[242:243], off
	s_add_u32 m0, s15, 0x2000
	v_lshl_add_u64 v[242:243], v[132:133], 0, s[0:1]
	global_load_lds_dwordx4 v[242:243], off
	s_add_u32 m0, s15, 0xa000
	v_lshl_add_u64 v[242:243], v[140:141], 0, s[0:1]
	global_load_lds_dwordx4 v[242:243], off
	s_add_u32 m0, s15, 0x4000
	v_lshl_add_u64 v[242:243], v[134:135], 0, s[0:1]
	global_load_lds_dwordx4 v[242:243], off
	s_add_u32 m0, s15, 0xc000
	v_lshl_add_u64 v[242:243], v[142:143], 0, s[0:1]
	global_load_lds_dwordx4 v[242:243], off
	s_add_u32 m0, s15, 0x6000
	v_lshl_add_u64 v[242:243], v[136:137], 0, s[0:1]
	global_load_lds_dwordx4 v[242:243], off
	s_add_u32 m0, s15, 0xe000
	v_lshl_add_u64 v[242:243], v[144:145], 0, s[0:1]
	global_load_lds_dwordx4 v[242:243], off
	s_mov_b32 s15, 0
	v_add3_u32 v157, s15, v155, v153
	v_add3_u32 v209, s15, v155, v156
	v_add3_u32 v245, s15, v154, v152
	v_add3_u32 v247, s15, v154, v149
	v_add3_u32 v249, s15, v154, v147
	v_add3_u32 v244, s15, v154, v150
	v_add3_u32 v246, s15, v154, v151
	v_add3_u32 v248, s15, v154, v148
	v_add3_u32 v250, s15, v154, v146
	ds_read_b128 v[158:161], v157 offset:32768
	ds_read_b128 v[162:165], v157 offset:34816
	ds_read_b128 v[174:177], v209
	ds_read_b128 v[190:193], v244
	ds_read_b128 v[212:215], v245
	ds_read_b128 v[222:225], v246
	ds_read_b128 v[226:229], v247
	ds_read_b128 v[230:233], v248
	ds_read_b128 v[234:237], v249
	ds_read_b128 v[238:241], v250
	ds_read_b128 v[166:169], v157 offset:36864
	ds_read_b128 v[170:173], v157 offset:38912
	s_and_b32 s14, s9, 0x10000
	s_xor_b32 s15, s14, 0x10000
	v_add_u32_e32 v251, s15, v189
	s_nop 0
	v_readfirstlane_b32 s14, v251
	s_waitcnt lgkmcnt(8)
	v_mfma_f32_16x16x32_bf16 v[126:129], v[174:177], v[158:161], 0
	v_mfma_f32_16x16x32_bf16 v[122:125], v[174:177], v[162:165], 0
	v_mfma_f32_16x16x32_bf16 v[110:113], v[190:193], v[158:161], 0
	v_mfma_f32_16x16x32_bf16 v[106:109], v[190:193], v[162:165], 0
	s_waitcnt lgkmcnt(6)
	v_mfma_f32_16x16x32_bf16 v[94:97], v[212:215], v[158:161], 0
	v_mfma_f32_16x16x32_bf16 v[90:93], v[212:215], v[162:165], 0
	v_mfma_f32_16x16x32_bf16 v[78:81], v[222:225], v[158:161], 0
	v_mfma_f32_16x16x32_bf16 v[74:77], v[222:225], v[162:165], 0
	s_waitcnt lgkmcnt(4)
	v_mfma_f32_16x16x32_bf16 v[62:65], v[226:229], v[158:161], 0
	v_mfma_f32_16x16x32_bf16 v[58:61], v[226:229], v[162:165], 0
	v_mfma_f32_16x16x32_bf16 v[46:49], v[230:233], v[158:161], 0
	v_mfma_f32_16x16x32_bf16 v[42:45], v[230:233], v[162:165], 0
	s_waitcnt lgkmcnt(2)
	v_mfma_f32_16x16x32_bf16 v[30:33], v[234:237], v[158:161], 0
	v_mfma_f32_16x16x32_bf16 v[26:29], v[234:237], v[162:165], 0
	v_mfma_f32_16x16x32_bf16 v[14:17], v[238:241], v[158:161], 0
	v_mfma_f32_16x16x32_bf16 v[10:13], v[238:241], v[162:165], 0
	ds_read_b128 v[158:161], v157 offset:33792
	ds_read_b128 v[162:165], v157 offset:35840
	s_waitcnt lgkmcnt(2)
; #define MFMA16(a, b, c) __builtin_amdgcn_mfma_f32_16x16x32_bf16((a), (b), (c), 0, 0, 0)
; template <class Epi>
; DI void gemm8_tile(const bf16_t* __restrict__ Ab, int lda, const bf16_t* __restrict__ Bb, int ldb, int K, int brow, int bcol, const Epi epi,
;                    bool staged, bool has_next, const bf16_t* __restrict__ Abn, const bf16_t* __restrict__ Bbn) {
;     ...
;   for (int t = 0; t < nt; ++t) {
;     const int cur = t & 1;
;     const unsigned char* sa = smem + cur * G8_STAGE_B;
;     const unsigned char* sb = sa + G8_TILE_B;
; #pragma unroll
;     for (int ks = 0; ks < 2; ++ks) {
;       bf16x8 At[8], Bf[4];
;       Bf[0] = *(const bf16x8*)(sb + lds_byte2(wc * 64 + fr, ks * 32 + fq * 8));
;       At[0] = *(const bf16x8*)(sa + lds_byte2(wr * 128 + fr, ks * 32 + fq * 8));
; #pragma unroll
;       for (int n = 1; n < 4; ++n) Bf[n] = *(const bf16x8*)(sb + lds_byte2(wc * 64 + n * 16 + fr, ks * 32 + fq * 8));
; #pragma unroll
;       for (int m = 1; m < 8; ++m) At[m] = *(const bf16x8*)(sa + lds_byte2(wr * 128 + m * 16 + fr, ks * 32 + fq * 8));
;       {
;         __builtin_amdgcn_sched_barrier(0);
;         if (t + 1 < nt) { G8_STAGE_R(cur ^ 1, Ab + (t + 1) * 64, Bb + (t + 1) * 64, 2 * ks, 2 * ks + 2); }
;         else if (has_next) { G8_STAGE_R(0, Abn, Bbn, 2 * ks, 2 * ks + 2); }
;         __builtin_amdgcn_sched_barrier(0);
;       }
; #pragma unroll
;       for (int m = 0; m < 8; ++m)
; #pragma unroll
;         for (int n = 0; n < 4; ++n) acc[m][n] = MFMA16(At[m], Bf[n], acc[m][n]);
;       __builtin_amdgcn_sched_barrier(0);
;     }
;     asm volatile("s_waitcnt vmcnt(0)" ::: "memory");
;     __syncthreads();
	v_mfma_f32_16x16x32_bf16 v[118:121], v[174:177], v[166:169], 0
	v_mfma_f32_16x16x32_bf16 v[114:117], v[174:177], v[170:173], 0
	ds_read_b128 v[174:177], v209 offset:1024
	v_mfma_f32_16x16x32_bf16 v[102:105], v[190:193], v[166:169], 0
	v_mfma_f32_16x16x32_bf16 v[98:101], v[190:193], v[170:173], 0
	ds_read_b128 v[190:193], v244 offset:1024
	v_mfma_f32_16x16x32_bf16 v[86:89], v[212:215], v[166:169], 0
	v_mfma_f32_16x16x32_bf16 v[82:85], v[212:215], v[170:173], 0
	ds_read_b128 v[212:215], v245 offset:1024
	v_mfma_f32_16x16x32_bf16 v[70:73], v[222:225], v[166:169], 0
	v_mfma_f32_16x16x32_bf16 v[66:69], v[222:225], v[170:173], 0
	ds_read_b128 v[222:225], v246 offset:1024
	v_mfma_f32_16x16x32_bf16 v[54:57], v[226:229], v[166:169], 0
	v_mfma_f32_16x16x32_bf16 v[50:53], v[226:229], v[170:173], 0
	ds_read_b128 v[226:229], v247 offset:1024
	v_mfma_f32_16x16x32_bf16 v[38:41], v[230:233], v[166:169], 0
	v_mfma_f32_16x16x32_bf16 v[34:37], v[230:233], v[170:173], 0
	ds_read_b128 v[230:233], v248 offset:1024
	v_mfma_f32_16x16x32_bf16 v[22:25], v[234:237], v[166:169], 0
	v_mfma_f32_16x16x32_bf16 v[18:21], v[234:237], v[170:173], 0
	ds_read_b128 v[234:237], v249 offset:1024
	v_mfma_f32_16x16x32_bf16 v[6:9], v[238:241], v[166:169], 0
	v_mfma_f32_16x16x32_bf16 v[2:5], v[238:241], v[170:173], 0
	ds_read_b128 v[238:241], v250 offset:1024
	ds_read_b128 v[166:169], v157 offset:37888
	ds_read_b128 v[170:173], v157 offset:39936
	s_waitcnt lgkmcnt(8)
	v_mfma_f32_16x16x32_bf16 v[126:129], v[174:177], v[158:161], v[126:129]
	v_mfma_f32_16x16x32_bf16 v[122:125], v[174:177], v[162:165], v[122:125]
	v_add3_u32 v157, s15, v155, v153
	v_mfma_f32_16x16x32_bf16 v[110:113], v[190:193], v[158:161], v[110:113]
	v_mfma_f32_16x16x32_bf16 v[106:109], v[190:193], v[162:165], v[106:109]
	v_add3_u32 v209, s15, v155, v156
	s_waitcnt lgkmcnt(6)
	v_mfma_f32_16x16x32_bf16 v[94:97], v[212:215], v[158:161], v[94:97]
	v_mfma_f32_16x16x32_bf16 v[90:93], v[212:215], v[162:165], v[90:93]
	v_add3_u32 v245, s15, v154, v152
	v_mfma_f32_16x16x32_bf16 v[78:81], v[222:225], v[158:161], v[78:81]
	v_mfma_f32_16x16x32_bf16 v[74:77], v[222:225], v[162:165], v[74:77]
	v_add3_u32 v247, s15, v154, v149
	s_waitcnt lgkmcnt(4)
	v_mfma_f32_16x16x32_bf16 v[62:65], v[226:229], v[158:161], v[62:65]
	v_mfma_f32_16x16x32_bf16 v[58:61], v[226:229], v[162:165], v[58:61]
	v_add3_u32 v249, s15, v154, v147
	v_mfma_f32_16x16x32_bf16 v[46:49], v[230:233], v[158:161], v[46:49]
	v_mfma_f32_16x16x32_bf16 v[42:45], v[230:233], v[162:165], v[42:45]
	v_add3_u32 v244, s15, v154, v150
	s_waitcnt lgkmcnt(2)
	v_mfma_f32_16x16x32_bf16 v[30:33], v[234:237], v[158:161], v[30:33]
	v_mfma_f32_16x16x32_bf16 v[26:29], v[234:237], v[162:165], v[26:29]
	v_add3_u32 v246, s15, v154, v151
	v_mfma_f32_16x16x32_bf16 v[14:17], v[238:241], v[158:161], v[14:17]
	v_mfma_f32_16x16x32_bf16 v[10:13], v[238:241], v[162:165], v[10:13]
	v_add3_u32 v248, s15, v154, v148
	v_add3_u32 v250, s15, v154, v146
	s_waitcnt vmcnt(0) lgkmcnt(0)
	s_barrier
	s_add_u32 s0, s0, 0x80
	s_addc_u32 s1, s1, 0
	s_add_i32 s9, s9, 0x10000
	s_xor_b32 s15, s14, 0x10000
	ds_read_b128 v[158:161], v157 offset:32768
	ds_read_b128 v[162:165], v157 offset:34816
	v_mfma_f32_16x16x32_bf16 v[118:121], v[174:177], v[166:169], v[118:121]
	v_mfma_f32_16x16x32_bf16 v[114:117], v[174:177], v[170:173], v[114:117]
	ds_read_b128 v[174:177], v209
	s_mov_b32 m0, s15
	v_lshl_add_u64 v[242:243], v[130:131], 0, s[0:1]
	global_load_lds_dwordx4 v[242:243], off
	v_mfma_f32_16x16x32_bf16 v[102:105], v[190:193], v[166:169], v[102:105]
	v_mfma_f32_16x16x32_bf16 v[98:101], v[190:193], v[170:173], v[98:101]
	ds_read_b128 v[190:193], v244
	s_add_u32 m0, s15, 0x8000
	v_lshl_add_u64 v[242:243], v[138:139], 0, s[0:1]
	global_load_lds_dwordx4 v[242:243], off
	v_mfma_f32_16x16x32_bf16 v[86:89], v[212:215], v[166:169], v[86:89]
	v_mfma_f32_16x16x32_bf16 v[82:85], v[212:215], v[170:173], v[82:85]
	ds_read_b128 v[212:215], v245
	s_add_u32 m0, s15, 0x2000
	v_lshl_add_u64 v[242:243], v[132:133], 0, s[0:1]
	global_load_lds_dwordx4 v[242:243], off
	v_mfma_f32_16x16x32_bf16 v[70:73], v[222:225], v[166:169], v[70:73]
	v_mfma_f32_16x16x32_bf16 v[66:69], v[222:225], v[170:173], v[66:69]
	ds_read_b128 v[222:225], v246
	s_add_u32 m0, s15, 0xa000
	v_lshl_add_u64 v[242:243], v[140:141], 0, s[0:1]
	global_load_lds_dwordx4 v[242:243], off
	v_mfma_f32_16x16x32_bf16 v[54:57], v[226:229], v[166:169], v[54:57]
	v_mfma_f32_16x16x32_bf16 v[50:53], v[226:229], v[170:173], v[50:53]
	ds_read_b128 v[226:229], v247
	s_add_u32 m0, s15, 0x4000
	v_lshl_add_u64 v[242:243], v[134:135], 0, s[0:1]
	global_load_lds_dwordx4 v[242:243], off
	v_mfma_f32_16x16x32_bf16 v[38:41], v[230:233], v[166:169], v[38:41]
	v_mfma_f32_16x16x32_bf16 v[34:37], v[230:233], v[170:173], v[34:37]
	ds_read_b128 v[230:233], v248
	s_add_u32 m0, s15, 0xc000
	v_lshl_add_u64 v[242:243], v[142:143], 0, s[0:1]
	global_load_lds_dwordx4 v[242:243], off
	v_mfma_f32_16x16x32_bf16 v[22:25], v[234:237], v[166:169], v[22:25]
	v_mfma_f32_16x16x32_bf16 v[18:21], v[234:237], v[170:173], v[18:21]
	ds_read_b128 v[234:237], v249
	s_add_u32 m0, s15, 0x6000
	v_lshl_add_u64 v[242:243], v[136:137], 0, s[0:1]
	global_load_lds_dwordx4 v[242:243], off
	v_mfma_f32_16x16x32_bf16 v[6:9], v[238:241], v[166:169], v[6:9]
	v_mfma_f32_16x16x32_bf16 v[2:5], v[238:241], v[170:173], v[2:5]
	ds_read_b128 v[238:241], v250
	s_add_u32 m0, s15, 0xe000
	v_lshl_add_u64 v[242:243], v[144:145], 0, s[0:1]
	global_load_lds_dwordx4 v[242:243], off
	ds_read_b128 v[166:169], v157 offset:36864
	ds_read_b128 v[170:173], v157 offset:38912

; DI int opaque_tid512() { int t = threadIdx.x; asm volatile("" : "+v"(t)); return t; }
; #define MFMA16(a, b, c) __builtin_amdgcn_mfma_f32_16x16x32_bf16((a), (b), (c), 0, 0, 0)
; #define G8_STAGE(buf_, ap_, bp_) G8_STAGE_R(buf_, ap_, bp_, 0, 4)
; template <class Epi>
; DI void gemm8_tile(const bf16_t* __restrict__ Ab, int lda, const bf16_t* __restrict__ Bb, int ldb, int K, int brow, int bcol, const Epi epi,
;                    bool staged, bool has_next, const bf16_t* __restrict__ Abn, const bf16_t* __restrict__ Bbn) {
;   const int tid = opaque_tid512(), wid = tid >> 6, lane = tid & 63, wr = wid >> 2, wc = wid & 3, fr = lane & 15, fq = lane >> 4;
;   unsigned aoff[4], boff[4];
; #pragma unroll
;   for (int i = 0; i < 4; ++i) { int R, C; stage_rc2(wid * 1024 + i * 8192 + lane * 16, R, C); aoff[i] = (unsigned)R * (unsigned)lda + (unsigned)C; boff[i] = (unsigned)R * (unsigned)ldb + (unsigned)C; }
;     ...
;   f32x4 acc[8][4];
; #pragma unroll
;   for (int m = 0; m < 8; ++m)
; #pragma unroll
;     for (int n = 0; n < 4; ++n) acc[m][n] = (f32x4){0.f, 0.f, 0.f, 0.f};
;   const int nt = K / 64;
;   if (!staged) {
;     G8_STAGE(0, Ab, Bb);
;     asm volatile("s_waitcnt vmcnt(0)" ::: "memory");
;     __syncthreads();
;   }
;   for (int t = 0; t < nt; ++t) {
;     const int cur = t & 1;
;     const unsigned char* sa = smem + cur * G8_STAGE_B;
;     const unsigned char* sb = sa + G8_TILE_B;
; #pragma unroll
;     for (int ks = 0; ks < 2; ++ks) {
;       bf16x8 At[8], Bf[4];
;       Bf[0] = *(const bf16x8*)(sb + lds_byte2(wc * 64 + fr, ks * 32 + fq * 8));
;       At[0] = *(const bf16x8*)(sa + lds_byte2(wr * 128 + fr, ks * 32 + fq * 8));
; #pragma unroll
;       for (int n = 1; n < 4; ++n) Bf[n] = *(const bf16x8*)(sb + lds_byte2(wc * 64 + n * 16 + fr, ks * 32 + fq * 8));
; #pragma unroll
;       for (int m = 1; m < 8; ++m) At[m] = *(const bf16x8*)(sa + lds_byte2(wr * 128 + m * 16 + fr, ks * 32 + fq * 8));
;       {
;         __builtin_amdgcn_sched_barrier(0);
;         if (t + 1 < nt) { G8_STAGE_R(cur ^ 1, Ab + (t + 1) * 64, Bb + (t + 1) * 64, 2 * ks, 2 * ks + 2); }
;         else if (has_next) { G8_STAGE_R(0, Abn, Bbn, 2 * ks, 2 * ks + 2); }
;         __builtin_amdgcn_sched_barrier(0);
;       }
; #pragma unroll
;       for (int m = 0; m < 8; ++m)
; #pragma unroll
;         for (int n = 0; n < 4; ++n) acc[m][n] = MFMA16(At[m], Bf[n], acc[m][n]);
.LBB0_1672:
	v_readlane_b32 s0, v253, 23
	s_add_u32 s0, s0, s57
	v_readlane_b32 s1, v253, 24
	v_lshlrev_b64 v[212:213], 1, v[0:1]
	s_addc_u32 s1, s1, s58
	v_lshlrev_b64 v[214:215], 1, v[6:7]
	v_lshlrev_b64 v[146:147], 1, v[4:5]
	v_lshlrev_b64 v[148:149], 1, v[2:3]
	v_lshl_add_u64 v[130:131], s[0:1], 0, v[212:213]
	v_lshl_add_u64 v[132:133], s[0:1], 0, v[214:215]
	v_lshl_add_u64 v[134:135], s[0:1], 0, v[146:147]
	v_lshl_add_u64 v[136:137], s[0:1], 0, v[148:149]
	s_lshl_b32 s0, s55, 3
	s_add_i32 s0, s28, s0
	s_add_i32 s0, s0, s56
	s_lshl_b32 s1, s54, 3
	s_sub_i32 s0, s0, s1
	s_lshl_b32 s1, s0, 8
	s_mul_i32 s0, s0, 0x88000
	v_readlane_b32 s4, v253, 6
	v_and_b32_e32 v228, 63, v8
	v_and_b32_e32 v229, 3, v9
	v_ashrrev_i32_e32 v9, 8, v8
	v_and_b32_e32 v223, 15, v8
	v_and_b32_e32 v10, 48, v8
	v_lshlrev_b32_e32 v12, 2, v8
	v_lshlrev_b32_e32 v8, 6, v8
	s_mul_hi_i32 s1, s1, 0x880
	s_add_u32 s0, s4, s0
	v_readlane_b32 s4, v253, 7
	v_lshlrev_b32_e32 v11, 6, v223
	v_and_b32_e32 v12, 32, v12
	v_lshlrev_b32_e32 v158, 14, v9
	v_and_b32_e32 v8, 0x3c0, v8
	s_addc_u32 s1, s4, s1
	v_lshlrev_b32_e32 v151, 13, v229
	v_bitop3_b32 v153, v11, v12, v10 bitop3:0x36
	v_lshlrev_b32_e32 v230, 7, v9
	v_or_b32_e32 v150, 0x800, v158
	v_bitop3_b32 v152, v8, v12, v10 bitop3:0x36
	v_or_b32_e32 v167, 0x1000, v158
	v_or_b32_e32 v166, 0x1800, v158
	v_or_b32_e32 v165, 0x2000, v158
	v_or_b32_e32 v164, 0x2800, v158
	v_or_b32_e32 v163, 0x3000, v158
	v_or_b32_e32 v162, 0x3800, v158
	v_lshl_add_u64 v[138:139], s[0:1], 0, v[212:213]
	v_lshl_add_u64 v[140:141], s[0:1], 0, v[214:215]
	v_lshl_add_u64 v[142:143], s[0:1], 0, v[146:147]
	v_lshl_add_u64 v[144:145], s[0:1], 0, v[148:149]
	s_mov_b64 s[0:1], 0
	s_mov_b32 s14, 0
	v_add_u32_e32 v244, 0x10000, v157
	s_nop 0
	v_readfirstlane_b32 s38, v244
	s_mov_b32 m0, s38
	v_lshl_add_u64 v[160:161], v[144:145], 0, s[0:1]
	global_load_lds_dwordx4 v[160:161], off
	s_add_u32 m0, s38, 0x8000
	v_lshl_add_u64 v[160:161], v[136:137], 0, s[0:1]
	global_load_lds_dwordx4 v[160:161], off
	s_add_u32 m0, s38, 0x2000
	v_lshl_add_u64 v[160:161], v[142:143], 0, s[0:1]
	global_load_lds_dwordx4 v[160:161], off
	s_add_u32 m0, s38, 0xa000
	v_lshl_add_u64 v[160:161], v[134:135], 0, s[0:1]
	global_load_lds_dwordx4 v[160:161], off
	s_add_u32 m0, s38, 0x4000
	v_lshl_add_u64 v[160:161], v[140:141], 0, s[0:1]
	global_load_lds_dwordx4 v[160:161], off
	s_add_u32 m0, s38, 0xc000
	v_lshl_add_u64 v[160:161], v[132:133], 0, s[0:1]
	global_load_lds_dwordx4 v[160:161], off
	s_add_u32 m0, s38, 0x6000
	v_lshl_add_u64 v[160:161], v[138:139], 0, s[0:1]
	global_load_lds_dwordx4 v[160:161], off
	s_add_u32 m0, s38, 0xe000
	v_lshl_add_u64 v[160:161], v[130:131], 0, s[0:1]
	global_load_lds_dwordx4 v[160:161], off
	s_mov_b32 s38, 0
	v_add3_u32 v0, s38, v153, v151
	v_add3_u32 v159, s38, v153, v158
	v_add3_u32 v209, s38, v152, v167
	v_add3_u32 v240, s38, v152, v165
	v_add3_u32 v242, s38, v152, v163
	v_add3_u32 v208, s38, v152, v150
	v_add3_u32 v231, s38, v152, v166
	v_add3_u32 v241, s38, v152, v164
	v_add3_u32 v243, s38, v152, v162
	ds_read_b128 v[168:171], v0 offset:32768
	ds_read_b128 v[172:175], v0 offset:34816
	ds_read_b128 v[184:187], v159
	ds_read_b128 v[188:191], v208
	ds_read_b128 v[192:195], v209
	ds_read_b128 v[196:199], v231
	ds_read_b128 v[200:203], v240
	ds_read_b128 v[204:207], v241
	ds_read_b128 v[232:235], v242
	ds_read_b128 v[236:239], v243
	ds_read_b128 v[176:179], v0 offset:36864
	ds_read_b128 v[180:183], v0 offset:38912
	s_and_b32 s15, s14, 0x10000
	s_xor_b32 s38, s15, 0x10000
	v_add_u32_e32 v244, s38, v157
	s_nop 0
	v_readfirstlane_b32 s15, v244
	s_waitcnt lgkmcnt(8)
	v_mfma_f32_16x16x32_bf16 v[126:129], v[184:187], v[168:171], 0
	v_mfma_f32_16x16x32_bf16 v[122:125], v[184:187], v[172:175], 0
	v_mfma_f32_16x16x32_bf16 v[110:113], v[188:191], v[168:171], 0
	v_mfma_f32_16x16x32_bf16 v[106:109], v[188:191], v[172:175], 0
	s_waitcnt lgkmcnt(6)
	v_mfma_f32_16x16x32_bf16 v[94:97], v[192:195], v[168:171], 0
	v_mfma_f32_16x16x32_bf16 v[90:93], v[192:195], v[172:175], 0
	v_mfma_f32_16x16x32_bf16 v[78:81], v[196:199], v[168:171], 0
	v_mfma_f32_16x16x32_bf16 v[74:77], v[196:199], v[172:175], 0
	s_waitcnt lgkmcnt(4)
	v_mfma_f32_16x16x32_bf16 v[62:65], v[200:203], v[168:171], 0
	v_mfma_f32_16x16x32_bf16 v[58:61], v[200:203], v[172:175], 0
	v_mfma_f32_16x16x32_bf16 v[46:49], v[204:207], v[168:171], 0
	v_mfma_f32_16x16x32_bf16 v[42:45], v[204:207], v[172:175], 0
	s_waitcnt lgkmcnt(2)
	v_mfma_f32_16x16x32_bf16 v[30:33], v[232:235], v[168:171], 0
	v_mfma_f32_16x16x32_bf16 v[26:29], v[232:235], v[172:175], 0
	v_mfma_f32_16x16x32_bf16 v[14:17], v[236:239], v[168:171], 0
	v_mfma_f32_16x16x32_bf16 v[10:13], v[236:239], v[172:175], 0
	ds_read_b128 v[168:171], v0 offset:33792
	ds_read_b128 v[172:175], v0 offset:35840
	s_waitcnt lgkmcnt(2)
; #define MFMA16(a, b, c) __builtin_amdgcn_mfma_f32_16x16x32_bf16((a), (b), (c), 0, 0, 0)
; template <class Epi>
; DI void gemm8_tile(const bf16_t* __restrict__ Ab, int lda, const bf16_t* __restrict__ Bb, int ldb, int K, int brow, int bcol, const Epi epi,
;                    bool staged, bool has_next, const bf16_t* __restrict__ Abn, const bf16_t* __restrict__ Bbn) {
;     ...
;   for (int t = 0; t < nt; ++t) {
;     const int cur = t & 1;
;     const unsigned char* sa = smem + cur * G8_STAGE_B;
;     const unsigned char* sb = sa + G8_TILE_B;
; #pragma unroll
;     for (int ks = 0; ks < 2; ++ks) {
;       bf16x8 At[8], Bf[4];
;       Bf[0] = *(const bf16x8*)(sb + lds_byte2(wc * 64 + fr, ks * 32 + fq * 8));
;       At[0] = *(const bf16x8*)(sa + lds_byte2(wr * 128 + fr, ks * 32 + fq * 8));
; #pragma unroll
;       for (int n = 1; n < 4; ++n) Bf[n] = *(const bf16x8*)(sb + lds_byte2(wc * 64 + n * 16 + fr, ks * 32 + fq * 8));
; #pragma unroll
;       for (int m = 1; m < 8; ++m) At[m] = *(const bf16x8*)(sa + lds_byte2(wr * 128 + m * 16 + fr, ks * 32 + fq * 8));
;       {
;         __builtin_amdgcn_sched_barrier(0);
;         if (t + 1 < nt) { G8_STAGE_R(cur ^ 1, Ab + (t + 1) * 64, Bb + (t + 1) * 64, 2 * ks, 2 * ks + 2); }
;         else if (has_next) { G8_STAGE_R(0, Abn, Bbn, 2 * ks, 2 * ks + 2); }
;         __builtin_amdgcn_sched_barrier(0);
;       }
; #pragma unroll
;       for (int m = 0; m < 8; ++m)
; #pragma unroll
;         for (int n = 0; n < 4; ++n) acc[m][n] = MFMA16(At[m], Bf[n], acc[m][n]);
;       __builtin_amdgcn_sched_barrier(0);
;     }
;     asm volatile("s_waitcnt vmcnt(0)" ::: "memory");
;     __syncthreads();
	v_mfma_f32_16x16x32_bf16 v[118:121], v[184:187], v[176:179], 0
	v_mfma_f32_16x16x32_bf16 v[114:117], v[184:187], v[180:183], 0
	ds_read_b128 v[184:187], v159 offset:1024
	v_mfma_f32_16x16x32_bf16 v[102:105], v[188:191], v[176:179], 0
	v_mfma_f32_16x16x32_bf16 v[98:101], v[188:191], v[180:183], 0
	ds_read_b128 v[188:191], v208 offset:1024
	v_mfma_f32_16x16x32_bf16 v[86:89], v[192:195], v[176:179], 0
	v_mfma_f32_16x16x32_bf16 v[82:85], v[192:195], v[180:183], 0
	ds_read_b128 v[192:195], v209 offset:1024
	v_mfma_f32_16x16x32_bf16 v[70:73], v[196:199], v[176:179], 0
	v_mfma_f32_16x16x32_bf16 v[66:69], v[196:199], v[180:183], 0
	ds_read_b128 v[196:199], v231 offset:1024
	v_mfma_f32_16x16x32_bf16 v[54:57], v[200:203], v[176:179], 0
	v_mfma_f32_16x16x32_bf16 v[50:53], v[200:203], v[180:183], 0
	ds_read_b128 v[200:203], v240 offset:1024
	v_mfma_f32_16x16x32_bf16 v[38:41], v[204:207], v[176:179], 0
	v_mfma_f32_16x16x32_bf16 v[34:37], v[204:207], v[180:183], 0
	ds_read_b128 v[204:207], v241 offset:1024
	v_mfma_f32_16x16x32_bf16 v[22:25], v[232:235], v[176:179], 0
	v_mfma_f32_16x16x32_bf16 v[18:21], v[232:235], v[180:183], 0
	ds_read_b128 v[232:235], v242 offset:1024
	v_mfma_f32_16x16x32_bf16 v[6:9], v[236:239], v[176:179], 0
	v_mfma_f32_16x16x32_bf16 v[2:5], v[236:239], v[180:183], 0
	ds_read_b128 v[236:239], v243 offset:1024
	ds_read_b128 v[176:179], v0 offset:37888
	ds_read_b128 v[180:183], v0 offset:39936
	s_waitcnt lgkmcnt(8)
	v_mfma_f32_16x16x32_bf16 v[126:129], v[184:187], v[168:171], v[126:129]
	v_mfma_f32_16x16x32_bf16 v[122:125], v[184:187], v[172:175], v[122:125]
	v_add3_u32 v0, s38, v153, v151
	v_mfma_f32_16x16x32_bf16 v[110:113], v[188:191], v[168:171], v[110:113]
	v_mfma_f32_16x16x32_bf16 v[106:109], v[188:191], v[172:175], v[106:109]
	v_add3_u32 v159, s38, v153, v158
	s_waitcnt lgkmcnt(6)
	v_mfma_f32_16x16x32_bf16 v[94:97], v[192:195], v[168:171], v[94:97]
	v_mfma_f32_16x16x32_bf16 v[90:93], v[192:195], v[172:175], v[90:93]
	v_add3_u32 v209, s38, v152, v167
	v_mfma_f32_16x16x32_bf16 v[78:81], v[196:199], v[168:171], v[78:81]
	v_mfma_f32_16x16x32_bf16 v[74:77], v[196:199], v[172:175], v[74:77]
	v_add3_u32 v240, s38, v152, v165
	s_waitcnt lgkmcnt(4)
	v_mfma_f32_16x16x32_bf16 v[62:65], v[200:203], v[168:171], v[62:65]
	v_mfma_f32_16x16x32_bf16 v[58:61], v[200:203], v[172:175], v[58:61]
	v_add3_u32 v242, s38, v152, v163
	v_mfma_f32_16x16x32_bf16 v[46:49], v[204:207], v[168:171], v[46:49]
	v_mfma_f32_16x16x32_bf16 v[42:45], v[204:207], v[172:175], v[42:45]
	v_add3_u32 v208, s38, v152, v150
	s_waitcnt lgkmcnt(2)
	v_mfma_f32_16x16x32_bf16 v[30:33], v[232:235], v[168:171], v[30:33]
	v_mfma_f32_16x16x32_bf16 v[26:29], v[232:235], v[172:175], v[26:29]
	v_add3_u32 v231, s38, v152, v166
	v_mfma_f32_16x16x32_bf16 v[14:17], v[236:239], v[168:171], v[14:17]
	v_mfma_f32_16x16x32_bf16 v[10:13], v[236:239], v[172:175], v[10:13]
	v_add3_u32 v241, s38, v152, v164
	v_add3_u32 v243, s38, v152, v162
	s_waitcnt vmcnt(0) lgkmcnt(0)
	s_barrier
	s_add_u32 s0, s0, 0x80
	s_addc_u32 s1, s1, 0
	s_add_i32 s14, s14, 0x10000
	s_xor_b32 s38, s15, 0x10000
	ds_read_b128 v[168:171], v0 offset:32768
	ds_read_b128 v[172:175], v0 offset:34816
	v_mfma_f32_16x16x32_bf16 v[118:121], v[184:187], v[176:179], v[118:121]
	v_mfma_f32_16x16x32_bf16 v[114:117], v[184:187], v[180:183], v[114:117]
	ds_read_b128 v[184:187], v159
	s_mov_b32 m0, s38
	v_lshl_add_u64 v[160:161], v[144:145], 0, s[0:1]
	global_load_lds_dwordx4 v[160:161], off
	v_mfma_f32_16x16x32_bf16 v[102:105], v[188:191], v[176:179], v[102:105]
	v_mfma_f32_16x16x32_bf16 v[98:101], v[188:191], v[180:183], v[98:101]
	ds_read_b128 v[188:191], v208
	s_add_u32 m0, s38, 0x8000
	v_lshl_add_u64 v[160:161], v[136:137], 0, s[0:1]
	global_load_lds_dwordx4 v[160:161], off
	v_mfma_f32_16x16x32_bf16 v[86:89], v[192:195], v[176:179], v[86:89]
	v_mfma_f32_16x16x32_bf16 v[82:85], v[192:195], v[180:183], v[82:85]
	ds_read_b128 v[192:195], v209
	s_add_u32 m0, s38, 0x2000
	v_lshl_add_u64 v[160:161], v[142:143], 0, s[0:1]
	global_load_lds_dwordx4 v[160:161], off
	v_mfma_f32_16x16x32_bf16 v[70:73], v[196:199], v[176:179], v[70:73]
	v_mfma_f32_16x16x32_bf16 v[66:69], v[196:199], v[180:183], v[66:69]
	ds_read_b128 v[196:199], v231
	s_add_u32 m0, s38, 0xa000
	v_lshl_add_u64 v[160:161], v[134:135], 0, s[0:1]
	global_load_lds_dwordx4 v[160:161], off
	v_mfma_f32_16x16x32_bf16 v[54:57], v[200:203], v[176:179], v[54:57]
	v_mfma_f32_16x16x32_bf16 v[50:53], v[200:203], v[180:183], v[50:53]
	ds_read_b128 v[200:203], v240
	s_add_u32 m0, s38, 0x4000
	v_lshl_add_u64 v[160:161], v[140:141], 0, s[0:1]
	global_load_lds_dwordx4 v[160:161], off
	v_mfma_f32_16x16x32_bf16 v[38:41], v[204:207], v[176:179], v[38:41]
	v_mfma_f32_16x16x32_bf16 v[34:37], v[204:207], v[180:183], v[34:37]
	ds_read_b128 v[204:207], v241
	s_add_u32 m0, s38, 0xc000
	v_lshl_add_u64 v[160:161], v[132:133], 0, s[0:1]
	global_load_lds_dwordx4 v[160:161], off
	v_mfma_f32_16x16x32_bf16 v[22:25], v[232:235], v[176:179], v[22:25]
	v_mfma_f32_16x16x32_bf16 v[18:21], v[232:235], v[180:183], v[18:21]
	ds_read_b128 v[232:235], v242
	s_add_u32 m0, s38, 0x6000
	v_lshl_add_u64 v[160:161], v[138:139], 0, s[0:1]
	global_load_lds_dwordx4 v[160:161], off
	v_mfma_f32_16x16x32_bf16 v[6:9], v[236:239], v[176:179], v[6:9]
	v_mfma_f32_16x16x32_bf16 v[2:5], v[236:239], v[180:183], v[2:5]
	ds_read_b128 v[236:239], v243
	s_add_u32 m0, s38, 0xe000
	v_lshl_add_u64 v[160:161], v[130:131], 0, s[0:1]
	global_load_lds_dwordx4 v[160:161], off
	ds_read_b128 v[176:179], v0 offset:36864
	ds_read_b128 v[180:183], v0 offset:38912

; DI int opaque_tid512() { int t = threadIdx.x; asm volatile("" : "+v"(t)); return t; }
; #define MFMA16(a, b, c) __builtin_amdgcn_mfma_f32_16x16x32_bf16((a), (b), (c), 0, 0, 0)
; #define G8_STAGE(buf_, ap_, bp_) G8_STAGE_R(buf_, ap_, bp_, 0, 4)
; template <class Epi>
; DI void gemm8_tile(const bf16_t* __restrict__ Ab, int lda, const bf16_t* __restrict__ Bb, int ldb, int K, int brow, int bcol, const Epi epi,
;                    bool staged, bool has_next, const bf16_t* __restrict__ Abn, const bf16_t* __restrict__ Bbn) {
;   const int tid = opaque_tid512(), wid = tid >> 6, lane = tid & 63, wr = wid >> 2, wc = wid & 3, fr = lane & 15, fq = lane >> 4;
;   unsigned aoff[4], boff[4];
; #pragma unroll
;   for (int i = 0; i < 4; ++i) { int R, C; stage_rc2(wid * 1024 + i * 8192 + lane * 16, R, C); aoff[i] = (unsigned)R * (unsigned)lda + (unsigned)C; boff[i] = (unsigned)R * (unsigned)ldb + (unsigned)C; }
;     ...
;   f32x4 acc[8][4];
; #pragma unroll
;   for (int m = 0; m < 8; ++m)
; #pragma unroll
;     for (int n = 0; n < 4; ++n) acc[m][n] = (f32x4){0.f, 0.f, 0.f, 0.f};
;   const int nt = K / 64;
;   if (!staged) {
;     G8_STAGE(0, Ab, Bb);
;     asm volatile("s_waitcnt vmcnt(0)" ::: "memory");
;     __syncthreads();
;   }
;   for (int t = 0; t < nt; ++t) {
;     const int cur = t & 1;
;     const unsigned char* sa = smem + cur * G8_STAGE_B;
;     const unsigned char* sb = sa + G8_TILE_B;
; #pragma unroll
;     for (int ks = 0; ks < 2; ++ks) {
;       bf16x8 At[8], Bf[4];
;       Bf[0] = *(const bf16x8*)(sb + lds_byte2(wc * 64 + fr, ks * 32 + fq * 8));
;       At[0] = *(const bf16x8*)(sa + lds_byte2(wr * 128 + fr, ks * 32 + fq * 8));
; #pragma unroll
;       for (int n = 1; n < 4; ++n) Bf[n] = *(const bf16x8*)(sb + lds_byte2(wc * 64 + n * 16 + fr, ks * 32 + fq * 8));
; #pragma unroll
;       for (int m = 1; m < 8; ++m) At[m] = *(const bf16x8*)(sa + lds_byte2(wr * 128 + m * 16 + fr, ks * 32 + fq * 8));
;       {
;         __builtin_amdgcn_sched_barrier(0);
;         if (t + 1 < nt) { G8_STAGE_R(cur ^ 1, Ab + (t + 1) * 64, Bb + (t + 1) * 64, 2 * ks, 2 * ks + 2); }
;         else if (has_next) { G8_STAGE_R(0, Abn, Bbn, 2 * ks, 2 * ks + 2); }
;         __builtin_amdgcn_sched_barrier(0);
;       }
; #pragma unroll
;       for (int m = 0; m < 8; ++m)
; #pragma unroll
;         for (int n = 0; n < 4; ++n) acc[m][n] = MFMA16(At[m], Bf[n], acc[m][n]);
.LBB0_1694:
	s_lshl_b32 s0, s79, 3
	s_add_i32 s0, s28, s0
	s_add_i32 s0, s0, s81
	s_lshl_b32 s1, s78, 3
	s_sub_i32 s0, s0, s1
	s_lshl_b32 s1, s0, 8
	s_mul_i32 s0, s0, 0x168000
	s_mul_hi_i32 s1, s1, 0x1680
	s_add_u32 s0, s91, s0
	v_lshlrev_b64 v[178:179], 1, v[4:5]
	s_addc_u32 s1, s72, s1
	v_lshlrev_b64 v[180:181], 1, v[2:3]
	v_lshlrev_b64 v[194:195], 1, v[6:7]
	v_lshlrev_b64 v[196:197], 1, v[0:1]
	v_and_b32_e32 v198, 15, v8
	v_lshl_add_u64 v[130:131], s[0:1], 0, v[178:179]
	v_lshl_add_u64 v[132:133], s[0:1], 0, v[180:181]
	v_lshl_add_u64 v[134:135], s[0:1], 0, v[194:195]
	v_lshl_add_u64 v[136:137], s[0:1], 0, v[196:197]
	v_readlane_b32 s0, v253, 25
	v_and_b32_e32 v206, 63, v8
	v_ashrrev_i32_e32 v10, 8, v8
	v_and_b32_e32 v204, 3, v9
	v_and_b32_e32 v9, 48, v8
	v_lshlrev_b32_e32 v199, 2, v198
	v_lshlrev_b32_e32 v8, 6, v8
	s_add_u32 s0, s0, s84
	v_readlane_b32 s1, v253, 26
	v_lshlrev_b32_e32 v11, 6, v198
	v_and_b32_e32 v12, 32, v199
	v_lshlrev_b32_e32 v156, 14, v10
	v_and_b32_e32 v8, 0x3c0, v8
	s_addc_u32 s1, s1, s85
	v_lshlrev_b32_e32 v153, 13, v204
	v_bitop3_b32 v155, v11, v12, v9 bitop3:0x36
	v_lshlrev_b32_e32 v205, 7, v10
	v_or_b32_e32 v150, 0x800, v156
	v_bitop3_b32 v154, v8, v12, v9 bitop3:0x36
	v_or_b32_e32 v152, 0x1000, v156
	v_or_b32_e32 v151, 0x1800, v156
	v_or_b32_e32 v149, 0x2000, v156
	v_or_b32_e32 v148, 0x2800, v156
	v_or_b32_e32 v147, 0x3000, v156
	v_or_b32_e32 v146, 0x3800, v156
	v_lshl_add_u64 v[138:139], s[0:1], 0, v[178:179]
	v_lshl_add_u64 v[140:141], s[0:1], 0, v[180:181]
	v_lshl_add_u64 v[142:143], s[0:1], 0, v[194:195]
	v_lshl_add_u64 v[144:145], s[0:1], 0, v[196:197]
	s_mov_b64 s[0:1], 0
	s_mov_b32 s58, 0
	v_add_u32_e32 v244, 0x10000, v185
	s_nop 0
	v_readfirstlane_b32 s70, v244
	s_mov_b32 m0, s70
	v_lshl_add_u64 v[208:209], v[130:131], 0, s[0:1]
	global_load_lds_dwordx4 v[208:209], off
	s_add_u32 m0, s70, 0x8000
	v_lshl_add_u64 v[208:209], v[138:139], 0, s[0:1]
	global_load_lds_dwordx4 v[208:209], off
	s_add_u32 m0, s70, 0x2000
	v_lshl_add_u64 v[208:209], v[132:133], 0, s[0:1]
	global_load_lds_dwordx4 v[208:209], off
	s_add_u32 m0, s70, 0xa000
	v_lshl_add_u64 v[208:209], v[140:141], 0, s[0:1]
	global_load_lds_dwordx4 v[208:209], off
	s_add_u32 m0, s70, 0x4000
	v_lshl_add_u64 v[208:209], v[134:135], 0, s[0:1]
	global_load_lds_dwordx4 v[208:209], off
	s_add_u32 m0, s70, 0xc000
	v_lshl_add_u64 v[208:209], v[142:143], 0, s[0:1]
	global_load_lds_dwordx4 v[208:209], off
	s_add_u32 m0, s70, 0x6000
	v_lshl_add_u64 v[208:209], v[136:137], 0, s[0:1]
	global_load_lds_dwordx4 v[208:209], off
	s_add_u32 m0, s70, 0xe000
	v_lshl_add_u64 v[208:209], v[144:145], 0, s[0:1]
	global_load_lds_dwordx4 v[208:209], off
	s_mov_b32 s70, 0
	v_add3_u32 v0, s70, v155, v153
	v_add3_u32 v157, s70, v155, v156
	v_add3_u32 v238, s70, v154, v152
	v_add3_u32 v240, s70, v154, v149
	v_add3_u32 v242, s70, v154, v147
	v_add3_u32 v207, s70, v154, v150
	v_add3_u32 v239, s70, v154, v151
	v_add3_u32 v241, s70, v154, v148
	v_add3_u32 v243, s70, v154, v146
	ds_read_b128 v[158:161], v0 offset:32768
	ds_read_b128 v[162:165], v0 offset:34816
	ds_read_b128 v[174:177], v157
	ds_read_b128 v[186:189], v207
	ds_read_b128 v[190:193], v238
	ds_read_b128 v[212:215], v239
	ds_read_b128 v[222:225], v240
	ds_read_b128 v[226:229], v241
	ds_read_b128 v[230:233], v242
	ds_read_b128 v[234:237], v243
	ds_read_b128 v[166:169], v0 offset:36864
	ds_read_b128 v[170:173], v0 offset:38912
	s_and_b32 s59, s58, 0x10000
	s_xor_b32 s70, s59, 0x10000
	v_add_u32_e32 v244, s70, v185
	s_nop 0
	v_readfirstlane_b32 s59, v244
	s_waitcnt lgkmcnt(8)
	v_mfma_f32_16x16x32_bf16 v[126:129], v[174:177], v[158:161], 0
	v_mfma_f32_16x16x32_bf16 v[122:125], v[174:177], v[162:165], 0
	v_mfma_f32_16x16x32_bf16 v[110:113], v[186:189], v[158:161], 0
	v_mfma_f32_16x16x32_bf16 v[106:109], v[186:189], v[162:165], 0
	s_waitcnt lgkmcnt(6)
	v_mfma_f32_16x16x32_bf16 v[94:97], v[190:193], v[158:161], 0
	v_mfma_f32_16x16x32_bf16 v[90:93], v[190:193], v[162:165], 0
	v_mfma_f32_16x16x32_bf16 v[78:81], v[212:215], v[158:161], 0
	v_mfma_f32_16x16x32_bf16 v[74:77], v[212:215], v[162:165], 0
	s_waitcnt lgkmcnt(4)
	v_mfma_f32_16x16x32_bf16 v[62:65], v[222:225], v[158:161], 0
	v_mfma_f32_16x16x32_bf16 v[58:61], v[222:225], v[162:165], 0
	v_mfma_f32_16x16x32_bf16 v[46:49], v[226:229], v[158:161], 0
	v_mfma_f32_16x16x32_bf16 v[42:45], v[226:229], v[162:165], 0
	s_waitcnt lgkmcnt(2)
	v_mfma_f32_16x16x32_bf16 v[30:33], v[230:233], v[158:161], 0
	v_mfma_f32_16x16x32_bf16 v[26:29], v[230:233], v[162:165], 0
	v_mfma_f32_16x16x32_bf16 v[14:17], v[234:237], v[158:161], 0
	v_mfma_f32_16x16x32_bf16 v[10:13], v[234:237], v[162:165], 0
	ds_read_b128 v[158:161], v0 offset:33792
	ds_read_b128 v[162:165], v0 offset:35840
	s_waitcnt lgkmcnt(2)
; #define MFMA16(a, b, c) __builtin_amdgcn_mfma_f32_16x16x32_bf16((a), (b), (c), 0, 0, 0)
; template <class Epi>
; DI void gemm8_tile(const bf16_t* __restrict__ Ab, int lda, const bf16_t* __restrict__ Bb, int ldb, int K, int brow, int bcol, const Epi epi,
;                    bool staged, bool has_next, const bf16_t* __restrict__ Abn, const bf16_t* __restrict__ Bbn) {
;     ...
;   for (int t = 0; t < nt; ++t) {
;     const int cur = t & 1;
;     const unsigned char* sa = smem + cur * G8_STAGE_B;
;     const unsigned char* sb = sa + G8_TILE_B;
; #pragma unroll
;     for (int ks = 0; ks < 2; ++ks) {
;       bf16x8 At[8], Bf[4];
;       Bf[0] = *(const bf16x8*)(sb + lds_byte2(wc * 64 + fr, ks * 32 + fq * 8));
;       At[0] = *(const bf16x8*)(sa + lds_byte2(wr * 128 + fr, ks * 32 + fq * 8));
; #pragma unroll
;       for (int n = 1; n < 4; ++n) Bf[n] = *(const bf16x8*)(sb + lds_byte2(wc * 64 + n * 16 + fr, ks * 32 + fq * 8));
; #pragma unroll
;       for (int m = 1; m < 8; ++m) At[m] = *(const bf16x8*)(sa + lds_byte2(wr * 128 + m * 16 + fr, ks * 32 + fq * 8));
;       {
;         __builtin_amdgcn_sched_barrier(0);
;         if (t + 1 < nt) { G8_STAGE_R(cur ^ 1, Ab + (t + 1) * 64, Bb + (t + 1) * 64, 2 * ks, 2 * ks + 2); }
;         else if (has_next) { G8_STAGE_R(0, Abn, Bbn, 2 * ks, 2 * ks + 2); }
;         __builtin_amdgcn_sched_barrier(0);
;       }
; #pragma unroll
;       for (int m = 0; m < 8; ++m)
; #pragma unroll
;         for (int n = 0; n < 4; ++n) acc[m][n] = MFMA16(At[m], Bf[n], acc[m][n]);
;       __builtin_amdgcn_sched_barrier(0);
;     }
;     asm volatile("s_waitcnt vmcnt(0)" ::: "memory");
;     __syncthreads();
	v_mfma_f32_16x16x32_bf16 v[118:121], v[174:177], v[166:169], 0
	v_mfma_f32_16x16x32_bf16 v[114:117], v[174:177], v[170:173], 0
	ds_read_b128 v[174:177], v157 offset:1024
	v_mfma_f32_16x16x32_bf16 v[102:105], v[186:189], v[166:169], 0
	v_mfma_f32_16x16x32_bf16 v[98:101], v[186:189], v[170:173], 0
	ds_read_b128 v[186:189], v207 offset:1024
	v_mfma_f32_16x16x32_bf16 v[86:89], v[190:193], v[166:169], 0
	v_mfma_f32_16x16x32_bf16 v[82:85], v[190:193], v[170:173], 0
	ds_read_b128 v[190:193], v238 offset:1024
	v_mfma_f32_16x16x32_bf16 v[70:73], v[212:215], v[166:169], 0
	v_mfma_f32_16x16x32_bf16 v[66:69], v[212:215], v[170:173], 0
	ds_read_b128 v[212:215], v239 offset:1024
	v_mfma_f32_16x16x32_bf16 v[54:57], v[222:225], v[166:169], 0
	v_mfma_f32_16x16x32_bf16 v[50:53], v[222:225], v[170:173], 0
	ds_read_b128 v[222:225], v240 offset:1024
	v_mfma_f32_16x16x32_bf16 v[38:41], v[226:229], v[166:169], 0
	v_mfma_f32_16x16x32_bf16 v[34:37], v[226:229], v[170:173], 0
	ds_read_b128 v[226:229], v241 offset:1024
	v_mfma_f32_16x16x32_bf16 v[22:25], v[230:233], v[166:169], 0
	v_mfma_f32_16x16x32_bf16 v[18:21], v[230:233], v[170:173], 0
	ds_read_b128 v[230:233], v242 offset:1024
	v_mfma_f32_16x16x32_bf16 v[6:9], v[234:237], v[166:169], 0
	v_mfma_f32_16x16x32_bf16 v[2:5], v[234:237], v[170:173], 0
	ds_read_b128 v[234:237], v243 offset:1024
	ds_read_b128 v[166:169], v0 offset:37888
	ds_read_b128 v[170:173], v0 offset:39936
	s_waitcnt lgkmcnt(8)
	v_mfma_f32_16x16x32_bf16 v[126:129], v[174:177], v[158:161], v[126:129]
	v_mfma_f32_16x16x32_bf16 v[122:125], v[174:177], v[162:165], v[122:125]
	v_add3_u32 v0, s70, v155, v153
	v_mfma_f32_16x16x32_bf16 v[110:113], v[186:189], v[158:161], v[110:113]
	v_mfma_f32_16x16x32_bf16 v[106:109], v[186:189], v[162:165], v[106:109]
	v_add3_u32 v157, s70, v155, v156
	s_waitcnt lgkmcnt(6)
	v_mfma_f32_16x16x32_bf16 v[94:97], v[190:193], v[158:161], v[94:97]
	v_mfma_f32_16x16x32_bf16 v[90:93], v[190:193], v[162:165], v[90:93]
	v_add3_u32 v238, s70, v154, v152
	v_mfma_f32_16x16x32_bf16 v[78:81], v[212:215], v[158:161], v[78:81]
	v_mfma_f32_16x16x32_bf16 v[74:77], v[212:215], v[162:165], v[74:77]
	v_add3_u32 v240, s70, v154, v149
	s_waitcnt lgkmcnt(4)
	v_mfma_f32_16x16x32_bf16 v[62:65], v[222:225], v[158:161], v[62:65]
	v_mfma_f32_16x16x32_bf16 v[58:61], v[222:225], v[162:165], v[58:61]
	v_add3_u32 v242, s70, v154, v147
	v_mfma_f32_16x16x32_bf16 v[46:49], v[226:229], v[158:161], v[46:49]
	v_mfma_f32_16x16x32_bf16 v[42:45], v[226:229], v[162:165], v[42:45]
	v_add3_u32 v207, s70, v154, v150
	s_waitcnt lgkmcnt(2)
	v_mfma_f32_16x16x32_bf16 v[30:33], v[230:233], v[158:161], v[30:33]
	v_mfma_f32_16x16x32_bf16 v[26:29], v[230:233], v[162:165], v[26:29]
	v_add3_u32 v239, s70, v154, v151
	v_mfma_f32_16x16x32_bf16 v[14:17], v[234:237], v[158:161], v[14:17]
	v_mfma_f32_16x16x32_bf16 v[10:13], v[234:237], v[162:165], v[10:13]
	v_add3_u32 v241, s70, v154, v148
	v_add3_u32 v243, s70, v154, v146
	s_waitcnt vmcnt(0) lgkmcnt(0)
	s_barrier
	s_add_u32 s0, s0, 0x80
	s_addc_u32 s1, s1, 0
	s_add_i32 s58, s58, 0x10000
	s_xor_b32 s70, s59, 0x10000
	ds_read_b128 v[158:161], v0 offset:32768
	ds_read_b128 v[162:165], v0 offset:34816
	v_mfma_f32_16x16x32_bf16 v[118:121], v[174:177], v[166:169], v[118:121]
	v_mfma_f32_16x16x32_bf16 v[114:117], v[174:177], v[170:173], v[114:117]
	ds_read_b128 v[174:177], v157
	s_mov_b32 m0, s70
	v_lshl_add_u64 v[208:209], v[130:131], 0, s[0:1]
	global_load_lds_dwordx4 v[208:209], off
	v_mfma_f32_16x16x32_bf16 v[102:105], v[186:189], v[166:169], v[102:105]
	v_mfma_f32_16x16x32_bf16 v[98:101], v[186:189], v[170:173], v[98:101]
	ds_read_b128 v[186:189], v207
	s_add_u32 m0, s70, 0x8000
	v_lshl_add_u64 v[208:209], v[138:139], 0, s[0:1]
	global_load_lds_dwordx4 v[208:209], off
	v_mfma_f32_16x16x32_bf16 v[86:89], v[190:193], v[166:169], v[86:89]
	v_mfma_f32_16x16x32_bf16 v[82:85], v[190:193], v[170:173], v[82:85]
	ds_read_b128 v[190:193], v238
	s_add_u32 m0, s70, 0x2000
	v_lshl_add_u64 v[208:209], v[132:133], 0, s[0:1]
	global_load_lds_dwordx4 v[208:209], off
	v_mfma_f32_16x16x32_bf16 v[70:73], v[212:215], v[166:169], v[70:73]
	v_mfma_f32_16x16x32_bf16 v[66:69], v[212:215], v[170:173], v[66:69]
	ds_read_b128 v[212:215], v239
	s_add_u32 m0, s70, 0xa000
	v_lshl_add_u64 v[208:209], v[140:141], 0, s[0:1]
	global_load_lds_dwordx4 v[208:209], off
	v_mfma_f32_16x16x32_bf16 v[54:57], v[222:225], v[166:169], v[54:57]
	v_mfma_f32_16x16x32_bf16 v[50:53], v[222:225], v[170:173], v[50:53]
	ds_read_b128 v[222:225], v240
	s_add_u32 m0, s70, 0x4000
	v_lshl_add_u64 v[208:209], v[134:135], 0, s[0:1]
	global_load_lds_dwordx4 v[208:209], off
	v_mfma_f32_16x16x32_bf16 v[38:41], v[226:229], v[166:169], v[38:41]
	v_mfma_f32_16x16x32_bf16 v[34:37], v[226:229], v[170:173], v[34:37]
	ds_read_b128 v[226:229], v241
	s_add_u32 m0, s70, 0xc000
	v_lshl_add_u64 v[208:209], v[142:143], 0, s[0:1]
	global_load_lds_dwordx4 v[208:209], off
	v_mfma_f32_16x16x32_bf16 v[22:25], v[230:233], v[166:169], v[22:25]
	v_mfma_f32_16x16x32_bf16 v[18:21], v[230:233], v[170:173], v[18:21]
	ds_read_b128 v[230:233], v242
	s_add_u32 m0, s70, 0x6000
	v_lshl_add_u64 v[208:209], v[136:137], 0, s[0:1]
	global_load_lds_dwordx4 v[208:209], off
	v_mfma_f32_16x16x32_bf16 v[6:9], v[234:237], v[166:169], v[6:9]
	v_mfma_f32_16x16x32_bf16 v[2:5], v[234:237], v[170:173], v[2:5]
	ds_read_b128 v[234:237], v243
	s_add_u32 m0, s70, 0xe000
	v_lshl_add_u64 v[208:209], v[144:145], 0, s[0:1]
	global_load_lds_dwordx4 v[208:209], off
	ds_read_b128 v[166:169], v0 offset:36864
	ds_read_b128 v[170:173], v0 offset:38912
